# attention loop: K/V tiles staged by LDS-DMA instead of registers; loop unrolled x3 so ring-buffer LDS offsets are immediates
# speedup vs baseline: 1.0437x; 1.0313x over previous
; __device__ __forceinline__ void partialSM_fix(f32x16& p0) { for (int r = 0; r < 16; ++r) p0[r] = __builtin_amdgcn_exp2f(p0[r]); }
; __device__ __forceinline__ int v_st(int k, int c) { const int kk = (k & ~0xC) | ((k & 4) << 1) | ((k & 8) >> 1); return ((kk >> 3) * 4 + (c >> 5)) * 512 + ((kk & 7) * 32 + (c & 31)) * 2; }
; __device__ __forceinline__ int v_rd_base(int lane) { return ((lane & 3) << 3) | (((lane >> 2) & 3) << 6) | (((lane >> 4) & 1) << 5) | (((lane >> 5) & 1) << 8); }
; #define SLOAD(i, k0) do { sr_[i].vs0 = St::ld8(&Vh[(long)((k0) + sr) * LDK + sc]); sr_[i].vs1 = St::ld8(&Vh[(long)((k0) + 32 + sr) * LDK + sc]); \
;     sr_[i].ks0 = St::ld8(&Kh[(long)((k0) + sr) * LDK + sc]); sr_[i].ks1 = St::ld8(&Kh[(long)((k0) + 32 + sr) * LDK + sc]); } while (0)
; #define SWAIT() do { if constexpr (SDEPTH == 2) asm volatile("s_waitcnt vmcnt(4)" ::: "memory"); else asm volatile("s_waitcnt vmcnt(0)" ::: "memory"); } while (0)
; template <typename TQ>
; __device__ __forceinline__ void attn_dense_body(const TQ* __restrict__ Qb, const bf16* __restrict__ Kh, const bf16* __restrict__ Vh,
;                                                 bf16* __restrict__ Ob, int seq, char* lds) {
;     ...
;   const int tid = threadIdx.x, wid = tid >> 6, lane = tid & 63, r32 = lane & 31, hi = lane >> 5;
;   bf16* V_lds = (bf16*)lds; bf16* K_lds = (bf16*)(lds + 3 * SHM_V);
;   float* ws = (float*)(lds + 3 * SHM_V + 3 * SHM_K) + wid * 64; float* li_l = ws;
;     float l_reg = 0; f32x16 o[4] = {}; bf16x8 qr[8];
;   const TQ* Qw = Qb + (long)(wid * QBLK + r32) * LDQ + hi * 8;
; #pragma unroll
;   for (int d0 = 0; d0 < 8; ++d0) qr[d0] = SQ::tobf(SQ::ld8(Qw + d0 * 16));
;   const int sr = tid >> 4, sc = (tid & 15) * 8, vst0 = v_st(sr, sc), vst1 = v_st(32 + sr, sc);
;   const int vb0 = (int)(uintptr_t)V_lds + v_rd_base(lane);
;   struct { typename St::T vs0, vs1, ks0, ks1; } sr_[SDEPTH];
;     ...
;   f32x16 pA0, pA1, pB0, pB1; constexpr float alA = 1.f, alB = 1.f; bf16x8 pa0, pa1, pa2, pa3; const int NT = seq / KVBLK;
;   constexpr int SE = 0, SO = 0;
;   SLOAD(SE, 0); asm volatile("s_waitcnt vmcnt(0)" ::: "memory"); SWRITE(0, SE);
;   SLOAD(SO, KVBLK);
;   __syncthreads();
;   qkt(pA0, pA1, K_lds, qr, r32, hi); partialSM_fix(pA0);
;   SWAIT(); SWRITE(1, SO); SLOAD(SE, 2 * KVBLK);
;   __syncthreads();
.LBB0_1089:
	s_ashr_i32 s13, s12, 31
	s_lshl_b64 s[18:19], s[12:13], 12
	s_add_u32 s0, s40, s18
	s_addc_u32 s9, s41, s19
	s_lshl_b32 s52, s8, 7
	s_lshl_b32 s18, s8, 8
	s_add_u32 s54, s0, s18
	s_addc_u32 s55, s9, 0
	s_lshr_b32 s0, s8, 1
	s_lshl_b64 s[8:9], s[0:1], 22
	s_add_u32 s8, s8, s14
	s_addc_u32 s9, s9, s15
	s_lshl_b64 s[8:9], s[8:9], 1
	s_add_u32 s18, s3, s8
	s_addc_u32 s19, s38, s9
	s_add_u32 s20, s39, s8
	s_addc_u32 s21, s42, s9
	global_load_dwordx4 v[0:3], v192, s[20:21]
	global_load_dwordx4 v[4:7], v193, s[20:21]
	global_load_dwordx4 v[8:11], v192, s[18:19]
	global_load_dwordx4 v[12:15], v193, s[18:19]
	v_lshl_add_u64 v[16:17], s[54:55], 0, v[170:171]
	v_lshl_add_u64 v[16:17], v[16:17], 0, v[172:173]
	global_load_dwordx4 v[140:143], v[16:17], off
	global_load_dwordx4 v[136:139], v[16:17], off offset:32
	global_load_dwordx4 v[132:135], v[16:17], off offset:64
	global_load_dwordx4 v[128:131], v[16:17], off offset:96
	global_load_dwordx4 v[124:127], v[16:17], off offset:128
	global_load_dwordx4 v[120:123], v[16:17], off offset:160
	global_load_dwordx4 v[116:119], v[16:17], off offset:192
	global_load_dwordx4 v[112:115], v[16:17], off offset:224
	s_waitcnt vmcnt(0)
	global_load_dwordx4 v[50:53], v198, s[20:21]
	global_load_dwordx4 v[54:57], v198, s[18:19]
	global_load_dwordx4 v[58:61], v199, s[20:21]
	global_load_dwordx4 v[96:99], v199, s[18:19]
	v_add_u32_e32 v33, 0, v190
	v_add_u32_e32 v30, 0, v188
	v_add_u32_e32 v31, 0, v189
	s_lshl_b64 s[8:9], s[0:1], 23
	s_lshl_b64 s[14:15], s[14:15], 1
	s_add_u32 s8, s8, s14
	v_add_u32_e32 v62, s45, v180
	v_add_u32_e32 v63, s45, v181
	v_mov_b32_e32 v169, 0
	s_addc_u32 s9, s9, s15
	s_mov_b32 s54, 1
	s_mov_b32 s57, 0
	s_mov_b32 s56, 2
	s_mov_b32 s55, 4
	v_mov_b32_e32 v16, 0
	v_mov_b32_e32 v32, 0
	v_mov_b32_e32 v48, 0
	v_mov_b32_e32 v17, v169
	v_mov_b32_e32 v38, v169
	v_mov_b32_e32 v39, v169
	v_mov_b32_e32 v44, v169
	v_mov_b32_e32 v45, v169
	v_mov_b32_e32 v46, v169
	v_mov_b32_e32 v47, v169
	v_mov_b32_e32 v49, v169
	v_lshl_add_u64 v[174:175], v[166:167], 0, s[8:9]
	s_waitcnt vmcnt(15)
	ds_write_b128 v194, v[0:3]
	s_waitcnt vmcnt(14)
	ds_write_b128 v195, v[4:7]
	s_waitcnt vmcnt(13)
	ds_write_b128 v196, v[8:11] offset:49152
	s_waitcnt vmcnt(12)
	ds_write_b128 v197, v[12:15] offset:49152
	s_waitcnt lgkmcnt(0)
	s_barrier
	ds_read_b128 v[0:3], v200 offset:49152
	ds_read_b128 v[4:7], v200 offset:57344
	s_waitcnt vmcnt(11) lgkmcnt(1)
	v_mfma_f32_32x32x16_bf16 v[80:95], v[0:3], v[140:143], 0
	v_mov_b32_e32 v8, v169
	v_mov_b32_e32 v9, v169
	v_mov_b32_e32 v14, v169
	v_mov_b32_e32 v15, v169
	s_waitcnt lgkmcnt(0)
	v_mfma_f32_32x32x16_bf16 v[64:79], v[4:7], v[140:143], 0
	ds_read_b128 v[0:3], v201 offset:49152
	ds_read_b128 v[4:7], v201 offset:57344
	ds_read_b128 v[10:13], v203 offset:49152
	ds_read_b128 v[18:21], v203 offset:57344
	ds_read_b128 v[22:25], v204 offset:49152
	s_waitcnt vmcnt(10) lgkmcnt(4)
	v_mfma_f32_32x32x16_bf16 v[80:95], v[0:3], v[136:139], v[80:95]
	ds_read_b128 v[0:3], v202 offset:49152
	s_waitcnt lgkmcnt(4)
	v_mfma_f32_32x32x16_bf16 v[64:79], v[4:7], v[136:139], v[64:79]
	ds_read_b128 v[4:7], v202 offset:57344
	s_waitcnt vmcnt(9) lgkmcnt(0)
	v_mfma_f32_32x32x16_bf16 v[64:79], v[4:7], v[132:135], v[64:79]
	v_mov_b32_e32 v4, v169
	v_mov_b32_e32 v5, v169
	v_mov_b32_e32 v6, v169
	v_mov_b32_e32 v7, v169
	s_waitcnt vmcnt(8)
	v_mfma_f32_32x32x16_bf16 v[64:79], v[18:21], v[128:131], v[64:79]
	ds_read_b128 v[18:21], v204 offset:57344
	ds_read_b128 v[26:29], v30 offset:49152
	ds_read_b128 v[34:37], v30 offset:57344
	ds_read_b128 v[40:43], v31 offset:49152
	ds_read_b128 v[100:103], v31 offset:57344
	ds_read_b128 v[104:107], v33 offset:49152
	ds_read_b128 v[108:111], v33 offset:57344
	s_waitcnt vmcnt(0)
	global_load_dwordx4 v[144:147], v205, s[20:21]
	global_load_dwordx4 v[152:155], v205, s[18:19]
	global_load_dwordx4 v[148:151], v206, s[20:21]
	global_load_dwordx4 v[156:159], v206, s[18:19]
	v_mov_b32_e32 v30, v169
	v_mov_b32_e32 v31, v169
	v_mov_b32_e32 v33, v169
	v_mfma_f32_32x32x16_bf16 v[80:95], v[0:3], v[132:135], v[80:95]
	v_mov_b32_e32 v0, 0
	v_mov_b32_e32 v1, v169
	v_mov_b32_e32 v2, v169
	v_mov_b32_e32 v3, v169
	s_waitcnt vmcnt(7)
	ds_write_b128 v194, v[50:53] offset:16384
	s_waitcnt vmcnt(5)
	ds_write_b128 v195, v[58:61] offset:16384
	ds_write_b128 v62, v[54:57]
	s_waitcnt vmcnt(4)
	ds_write_b128 v63, v[96:99]
	v_mov_b32_e32 v50, v169
	v_mov_b32_e32 v51, v169
	v_mfma_f32_32x32x16_bf16 v[80:95], v[10:13], v[128:131], v[80:95]
	v_mov_b32_e32 v10, v169
	v_mov_b32_e32 v11, v169
	v_mov_b32_e32 v12, v169
	v_mov_b32_e32 v13, v169
	v_mov_b32_e32 v52, v169
	v_mov_b32_e32 v53, v169
	v_mov_b32_e32 v54, v169
	v_mfma_f32_32x32x16_bf16 v[80:95], v[22:25], v[124:127], v[80:95]
	v_mov_b32_e32 v22, v169
	v_mov_b32_e32 v23, v169
	v_mov_b32_e32 v24, v169
	v_mov_b32_e32 v25, v169
	v_mov_b32_e32 v55, v169
	v_mov_b32_e32 v56, v169
	v_mov_b32_e32 v57, v169
	s_waitcnt lgkmcnt(10)
	v_mfma_f32_32x32x16_bf16 v[64:79], v[18:21], v[124:127], v[64:79]
	v_mov_b32_e32 v18, v169
	v_mov_b32_e32 v19, v169
	v_mov_b32_e32 v20, v169
	v_mov_b32_e32 v21, v169
	v_mov_b32_e32 v58, v169
	v_mov_b32_e32 v59, v169
	v_mov_b32_e32 v60, v169
	s_waitcnt lgkmcnt(9)
	v_mfma_f32_32x32x16_bf16 v[80:95], v[26:29], v[120:123], v[80:95]
	v_mov_b32_e32 v26, v169
	v_mov_b32_e32 v27, v169
	v_mov_b32_e32 v28, v169
	v_mov_b32_e32 v29, v169
	v_mov_b32_e32 v61, v169
	v_mov_b32_e32 v62, v169
	v_mov_b32_e32 v63, v169
	s_waitcnt lgkmcnt(8)
	v_mfma_f32_32x32x16_bf16 v[64:79], v[34:37], v[120:123], v[64:79]
	v_mov_b32_e32 v34, v169
	v_mov_b32_e32 v35, v169
	v_mov_b32_e32 v36, v169
	v_mov_b32_e32 v37, v169
	s_waitcnt lgkmcnt(0)
	s_barrier
; #define SBAR() __builtin_amdgcn_sched_barrier(0)
; __device__ __forceinline__ void partialSM_fix(f32x16& p0) { for (int r = 0; r < 16; ++r) p0[r] = __builtin_amdgcn_exp2f(p0[r]); }
; #define SLOAD(i, k0) do { sr_[i].vs0 = St::ld8(&Vh[(long)((k0) + sr) * LDK + sc]); sr_[i].vs1 = St::ld8(&Vh[(long)((k0) + 32 + sr) * LDK + sc]); \
;     sr_[i].ks0 = St::ld8(&Kh[(long)((k0) + sr) * LDK + sc]); sr_[i].ks1 = St::ld8(&Kh[(long)((k0) + 32 + sr) * LDK + sc]); } while (0)
; #define SWAIT() do { if constexpr (SDEPTH == 2) asm volatile("s_waitcnt vmcnt(4)" ::: "memory"); else asm volatile("s_waitcnt vmcnt(0)" ::: "memory"); } while (0)
; template <typename TQ>
; __device__ __forceinline__ void attn_dense_body(const TQ* __restrict__ Qb, const bf16* __restrict__ Kh, const bf16* __restrict__ Vh,
;                                                 bf16* __restrict__ Ob, int seq, char* lds) {
;     ...
;   qkt(pA0, pA1, K_lds, qr, r32, hi); partialSM_fix(pA0);
;   SWAIT(); SWRITE(1, SO); SLOAD(SE, 2 * KVBLK);
;   __syncthreads();
;   int prev = 0, cur = 1, next = 2;
;   for (int j = 1; j + 1 < NT; j += 2) {
;     SBAR(); qkt(pB0, pB1, (bf16*)((char*)K_lds + cur * (int)SHM_K), qr, r32, hi);
;     finishSM(pA0, pA1, alA, l_reg, pa0, pa1, pa2, pa3); SBAR();
;     SWAIT(); SWRITE(next, SE);
;     if (j + 2 < NT) SLOAD(SO, (j + 2) * KVBLK); SBAR();
;     pv_d0(o, vb0 + prev * (int)SHM_V, pa0, pa1, pa2, pa3); partialSM_fix(pB0);
	v_mfma_f32_32x32x16_bf16 v[80:95], v[40:43], v[116:119], v[80:95]
	v_mov_b32_e32 v40, v169
	v_mov_b32_e32 v41, v169
	v_mov_b32_e32 v42, v169
	v_mov_b32_e32 v43, v169
	v_mfma_f32_32x32x16_bf16 v[64:79], v[100:103], v[116:119], v[64:79]
	v_mfma_f32_32x32x16_bf16 v[80:95], v[104:107], v[112:115], v[80:95]
	v_mfma_f32_32x32x16_bf16 v[64:79], v[108:111], v[112:115], v[64:79]
	s_nop 10
	v_exp_f32_e32 v224, v80
	v_exp_f32_e32 v225, v81
	v_exp_f32_e32 v226, v82
	v_exp_f32_e32 v227, v83
	v_exp_f32_e32 v228, v84
	v_exp_f32_e32 v229, v85
	v_exp_f32_e32 v230, v86
	v_exp_f32_e32 v231, v87
	v_exp_f32_e32 v232, v88
	v_exp_f32_e32 v233, v89
	v_exp_f32_e32 v234, v90
	v_exp_f32_e32 v235, v91
	v_exp_f32_e32 v236, v92
	v_exp_f32_e32 v237, v93
	v_exp_f32_e32 v238, v94
	v_exp_f32_e32 v239, v95
	s_waitcnt vmcnt(0)
	v_add_u32_e32 v144, 0xc000, v183
	v_add_u32_e32 v145, 0xc000, v184
	v_add_u32_e32 v146, 0xc000, v185
	v_add_u32_e32 v147, 0xc000, v186
	v_add_u32_e32 v148, 0xc000, v187
	v_add_u32_e32 v149, 0xc000, v188
	v_add_u32_e32 v150, 0xc000, v189
	v_add_u32_e32 v151, 0xc000, v190
	s_add_i32 s32, s53, 2
	s_add_u32 s90, s39, s8
	s_addc_u32 s91, s42, s9
	s_add_u32 s92, s3, s8
	s_addc_u32 s93, s38, s9
	s_add_u32 s90, s90, 0x8000
	s_addc_u32 s91, s91, 0
	s_add_u32 s92, s92, 0x8000
	s_addc_u32 s93, s93, 0
	v_readfirstlane_b32 s80, v160
	v_lshrrev_b32_e32 v248, 5, v162
	s_nop 3
	s_lshr_b32 s80, s80, 6
	s_lshl_b32 s80, s80, 11
	s_add_i32 s81, s80, 0x400
	s_add_i32 s82, s80, 0xc000
	s_add_i32 s83, s80, 0xc400
	v_and_b32_e32 v249, 31, v176
	v_lshrrev_b32_e32 v249, 2, v249
	v_lshl_add_u32 v249, v249, 8, v248
	v_lshrrev_b32_e32 v174, 5, v176
	v_lshl_add_u32 v249, v174, 6, v249
	v_and_b32_e32 v174, 3, v176
	v_lshl_add_u32 v249, v174, 4, v249
	v_lshrrev_b32_e32 v174, 4, v176
	v_lshrrev_b32_e32 v175, 16, v162
	v_and_b32_e32 v175, 1, v175
	v_lshl_or_b32 v175, v175, 3, v174
	v_and_b32_e32 v250, 15, v176
	v_xor_b32_e32 v175, v250, v175
	v_lshl_add_u32 v248, v174, 8, v248
	v_lshl_add_u32 v174, v175, 4, v248
	v_xor_b32_e32 v175, 64, v174
	v_add_u32_e32 v175, 0x400, v175
	s_add_i32 m0, s80, 0x8000
	s_add_u32 s96, s90, 0x80
	s_addc_u32 s97, s91, 0
	global_load_lds_dwordx4 v249, s[90:91]
	s_add_i32 m0, s81, 0x8000
	s_nop 0
	global_load_lds_dwordx4 v249, s[96:97]
	s_add_i32 m0, s82, 0x8000
	s_nop 0
	global_load_lds_dwordx4 v174, s[92:93]
	s_add_i32 m0, s83, 0x8000
	s_add_u32 s90, s90, 0x4000
	global_load_lds_dwordx4 v175, s[92:93]
	s_addc_u32 s91, s91, 0
	s_add_u32 s92, s92, 0x4000
	s_addc_u32 s93, s93, 0
	v_add_f32_e32 v254, v224, v226
	v_add_f32_e32 v255, v225, v227
	v_add_f32_e32 v254, v254, v228
	v_add_f32_e32 v255, v255, v229
	v_add_f32_e32 v254, v254, v230
	v_add_f32_e32 v255, v255, v231
	v_add_f32_e32 v254, v254, v232
	v_add_f32_e32 v255, v255, v233
	v_add_f32_e32 v254, v254, v234
	v_add_f32_e32 v255, v255, v235
	v_add_f32_e32 v254, v254, v236
	v_add_f32_e32 v255, v255, v237
	v_add_f32_e32 v254, v254, v238
	v_add_f32_e32 v255, v255, v239
	v_add_f32_e32 v254, v254, v255
	s_waitcnt lgkmcnt(0)
	ds_read_b128 v[208:211], v144 offset:16384
	ds_read_b128 v[212:215], v144 offset:24576
	ds_read_b128 v[216:219], v145 offset:16384
	ds_read_b128 v[220:223], v145 offset:24576
	ds_read_b128 v[240:243], v146 offset:16384
	ds_read_b128 v[244:247], v146 offset:24576
.Latt_loop:
	s_waitcnt lgkmcnt(4)
	v_mfma_f32_32x32x16_bf16 v[96:111], v[208:211], v[140:143], 0
	v_exp_f32_e32 v64, v64
	v_exp_f32_e32 v65, v65
	v_cvt_pk_bf16_f32 v224, v224, v225
	v_mfma_f32_32x32x16_bf16 v[80:95], v[212:215], v[140:143], 0
	ds_read_b128 v[208:211], v147 offset:16384
	ds_read_b128 v[212:215], v147 offset:24576
	v_exp_f32_e32 v66, v66
	v_exp_f32_e32 v67, v67
	v_cvt_pk_bf16_f32 v225, v226, v227
	s_waitcnt lgkmcnt(4)
	v_mfma_f32_32x32x16_bf16 v[96:111], v[216:219], v[136:139], v[96:111]
	v_exp_f32_e32 v68, v68
	v_exp_f32_e32 v69, v69
	v_cvt_pk_bf16_f32 v226, v228, v229
	v_mfma_f32_32x32x16_bf16 v[80:95], v[220:223], v[136:139], v[80:95]
	ds_read_b128 v[216:219], v148 offset:16384
	ds_read_b128 v[220:223], v148 offset:24576
	v_exp_f32_e32 v70, v70
	v_exp_f32_e32 v71, v71
	v_cvt_pk_bf16_f32 v227, v230, v231
	v_add_f32_e32 v251, v64, v66
	s_waitcnt lgkmcnt(4)
	v_mfma_f32_32x32x16_bf16 v[96:111], v[240:243], v[132:135], v[96:111]
	v_exp_f32_e32 v72, v72
	v_exp_f32_e32 v73, v73
	v_add_f32_e32 v253, v65, v67
	v_mfma_f32_32x32x16_bf16 v[80:95], v[244:247], v[132:135], v[80:95]
	ds_read_b128 v[240:243], v149 offset:16384
	ds_read_b128 v[244:247], v149 offset:24576
	v_exp_f32_e32 v74, v74
	v_exp_f32_e32 v75, v75
	v_add_f32_e32 v251, v251, v68
	s_waitcnt lgkmcnt(4)
	v_mfma_f32_32x32x16_bf16 v[96:111], v[208:211], v[128:131], v[96:111]
	v_exp_f32_e32 v76, v76
	v_exp_f32_e32 v77, v77
	v_add_f32_e32 v253, v253, v69
	v_cvt_pk_bf16_f32 v228, v232, v233
	v_mfma_f32_32x32x16_bf16 v[80:95], v[212:215], v[128:131], v[80:95]
	ds_read_b128 v[208:211], v150 offset:16384
	ds_read_b128 v[212:215], v150 offset:24576
	v_exp_f32_e32 v78, v78
	v_exp_f32_e32 v79, v79
	v_add_f32_e32 v251, v251, v70
	v_cvt_pk_bf16_f32 v229, v234, v235
	s_waitcnt lgkmcnt(4)
	v_mfma_f32_32x32x16_bf16 v[96:111], v[216:219], v[124:127], v[96:111]
	v_add_f32_e32 v253, v253, v71
	v_cvt_pk_bf16_f32 v230, v236, v237
	v_cvt_pk_bf16_f32 v231, v238, v239
	v_add_f32_e32 v251, v251, v72
	v_mfma_f32_32x32x16_bf16 v[80:95], v[220:223], v[124:127], v[80:95]
	ds_read_b128 v[216:219], v151 offset:16384
	ds_read_b128 v[220:223], v151 offset:24576
	v_add_f32_e32 v253, v253, v73
	v_cvt_pk_bf16_f32 v232, v64, v65
	v_cvt_pk_bf16_f32 v233, v66, v67
	s_waitcnt lgkmcnt(4)
; #define SBAR() __builtin_amdgcn_sched_barrier(0)
; __device__ __forceinline__ void partialSM_fix(f32x16& p0) { for (int r = 0; r < 16; ++r) p0[r] = __builtin_amdgcn_exp2f(p0[r]); }
; #define SLOAD(i, k0) do { sr_[i].vs0 = St::ld8(&Vh[(long)((k0) + sr) * LDK + sc]); sr_[i].vs1 = St::ld8(&Vh[(long)((k0) + 32 + sr) * LDK + sc]); \
;     sr_[i].ks0 = St::ld8(&Kh[(long)((k0) + sr) * LDK + sc]); sr_[i].ks1 = St::ld8(&Kh[(long)((k0) + 32 + sr) * LDK + sc]); } while (0)
; #define SWAIT() do { if constexpr (SDEPTH == 2) asm volatile("s_waitcnt vmcnt(4)" ::: "memory"); else asm volatile("s_waitcnt vmcnt(0)" ::: "memory"); } while (0)
; template <int D0> __device__ __forceinline__ void pv_one(f32x16& od, int vb, bf16x8 pa0, bf16x8 pa1, bf16x8 pa2, bf16x8 pa3) {
;   const s16x4 l0 = tr_read<v_rd_off(D0, 0, 0)>(vb), h0 = tr_read<v_rd_off(D0, 0, 1)>(vb), l1 = tr_read<v_rd_off(D0, 1, 0)>(vb), h1 = tr_read<v_rd_off(D0, 1, 1)>(vb);
;   const s16x4 l2 = tr_read<v_rd_off(D0, 2, 0)>(vb), h2 = tr_read<v_rd_off(D0, 2, 1)>(vb), l3 = tr_read<v_rd_off(D0, 3, 0)>(vb), h3 = tr_read<v_rd_off(D0, 3, 1)>(vb);
;   asm volatile("s_waitcnt lgkmcnt(0)" ::: "memory"); SBAR();
;     ...
;   od = __builtin_amdgcn_mfma_f32_32x32x16_bf16(pa0, PK(l0, h0), od, 0, 0, 0);
;   od = __builtin_amdgcn_mfma_f32_32x32x16_bf16(pa1, PK(l1, h1), od, 0, 0, 0);
;   od = __builtin_amdgcn_mfma_f32_32x32x16_bf16(pa2, PK(l2, h2), od, 0, 0, 0);
;   od = __builtin_amdgcn_mfma_f32_32x32x16_bf16(pa3, PK(l3, h3), od, 0, 0, 0);
;     ...
; }
; __device__ __forceinline__ void pv_d0(f32x16* o, int vb, bf16x8 pa0, bf16x8 pa1, bf16x8 pa2, bf16x8 pa3) {
;   pv_one<0>(o[0], vb, pa0, pa1, pa2, pa3); pv_one<1>(o[1], vb, pa0, pa1, pa2, pa3); pv_one<2>(o[2], vb, pa0, pa1, pa2, pa3); pv_one<3>(o[3], vb, pa0, pa1, pa2, pa3);
; }
; template <typename TQ>
; __device__ __forceinline__ void attn_dense_body(const TQ* __restrict__ Qb, const bf16* __restrict__ Kh, const bf16* __restrict__ Vh,
;                                                 bf16* __restrict__ Ob, int seq, char* lds) {
;     ...
;     SBAR(); qkt(pB0, pB1, (bf16*)((char*)K_lds + cur * (int)SHM_K), qr, r32, hi);
;     finishSM(pA0, pA1, alA, l_reg, pa0, pa1, pa2, pa3); SBAR();
;     SWAIT(); SWRITE(next, SE);
;     if (j + 2 < NT) SLOAD(SO, (j + 2) * KVBLK); SBAR();
;     pv_d0(o, vb0 + prev * (int)SHM_V, pa0, pa1, pa2, pa3); partialSM_fix(pB0);
;     __syncthreads();
	v_mfma_f32_32x32x16_bf16 v[96:111], v[240:243], v[120:123], v[96:111]
	v_add_f32_e32 v251, v251, v74
	v_cvt_pk_bf16_f32 v234, v68, v69
	v_cvt_pk_bf16_f32 v235, v70, v71
	v_mfma_f32_32x32x16_bf16 v[80:95], v[244:247], v[120:123], v[80:95]
	ds_read_b64_tr_b16 v[240:241], v179 offset:0
	ds_read_b64_tr_b16 v[242:243], v179 offset:2048
	ds_read_b64_tr_b16 v[244:245], v179 offset:4096
	ds_read_b64_tr_b16 v[246:247], v179 offset:6144
	v_add_f32_e32 v253, v253, v75
	v_add_f32_e32 v251, v251, v76
	v_cvt_pk_bf16_f32 v236, v72, v73
	v_cvt_pk_bf16_f32 v237, v74, v75
	s_waitcnt lgkmcnt(6)
	v_mfma_f32_32x32x16_bf16 v[96:111], v[208:211], v[116:119], v[96:111]
	v_add_f32_e32 v253, v253, v77
	v_add_f32_e32 v251, v251, v78
	v_mfma_f32_32x32x16_bf16 v[80:95], v[212:215], v[116:119], v[80:95]
	ds_read_b64_tr_b16 v[208:209], v179 offset:8192
	ds_read_b64_tr_b16 v[210:211], v179 offset:10240
	ds_read_b64_tr_b16 v[212:213], v179 offset:12288
	ds_read_b64_tr_b16 v[214:215], v179 offset:14336
	v_add_f32_e32 v253, v253, v79
	v_cvt_pk_bf16_f32 v238, v76, v77
	v_cvt_pk_bf16_f32 v239, v78, v79
	s_waitcnt lgkmcnt(8)
	v_mfma_f32_32x32x16_bf16 v[96:111], v[216:219], v[112:115], v[96:111]
	v_add_f32_e32 v251, v251, v253
	v_add_f32_e32 v254, v254, v251
	v_mfma_f32_32x32x16_bf16 v[80:95], v[220:223], v[112:115], v[80:95]
	ds_read_b64_tr_b16 v[216:217], v179 offset:512
	ds_read_b64_tr_b16 v[218:219], v179 offset:2560
	ds_read_b64_tr_b16 v[220:221], v179 offset:4608
	ds_read_b64_tr_b16 v[222:223], v179 offset:6656
	v_add_f32_e32 v169, v169, v254
	s_waitcnt lgkmcnt(10)
	v_mfma_f32_32x32x16_bf16 v[0:15], v[224:227], v[240:243], v[0:15]
	ds_read_b64_tr_b16 v[64:65], v179 offset:8704
	ds_read_b64_tr_b16 v[66:67], v179 offset:10752
	s_waitcnt lgkmcnt(10)
	v_mfma_f32_32x32x16_bf16 v[0:15], v[228:231], v[244:247], v[0:15]
	ds_read_b64_tr_b16 v[68:69], v179 offset:12800
	ds_read_b64_tr_b16 v[70:71], v179 offset:14848
	v_exp_f32_e32 v96, v96
	v_exp_f32_e32 v97, v97
	s_waitcnt lgkmcnt(10)
	v_mfma_f32_32x32x16_bf16 v[0:15], v[232:235], v[208:211], v[0:15]
	ds_read_b64_tr_b16 v[72:73], v179 offset:1024
	ds_read_b64_tr_b16 v[74:75], v179 offset:3072
	v_exp_f32_e32 v98, v98
	v_exp_f32_e32 v99, v99
	s_waitcnt lgkmcnt(10)
	v_mfma_f32_32x32x16_bf16 v[0:15], v[236:239], v[212:215], v[0:15]
	ds_read_b64_tr_b16 v[76:77], v179 offset:5120
	ds_read_b64_tr_b16 v[78:79], v179 offset:7168
	v_exp_f32_e32 v100, v100
	v_exp_f32_e32 v101, v101
	v_add_f32_e32 v254, v96, v98
	s_waitcnt lgkmcnt(10)
	v_mfma_f32_32x32x16_bf16 v[16:31], v[224:227], v[216:219], v[16:31]
	ds_read_b64_tr_b16 v[240:241], v179 offset:9216
	ds_read_b64_tr_b16 v[242:243], v179 offset:11264
	v_exp_f32_e32 v102, v102
	v_exp_f32_e32 v103, v103
	v_add_f32_e32 v255, v97, v99
	s_waitcnt lgkmcnt(10)
	v_mfma_f32_32x32x16_bf16 v[16:31], v[228:231], v[220:223], v[16:31]
	ds_read_b64_tr_b16 v[244:245], v179 offset:13312
	ds_read_b64_tr_b16 v[246:247], v179 offset:15360
	v_exp_f32_e32 v104, v104
	v_exp_f32_e32 v105, v105
	v_add_f32_e32 v254, v254, v100
	s_waitcnt lgkmcnt(10)
	v_mfma_f32_32x32x16_bf16 v[16:31], v[232:235], v[64:67], v[16:31]
	ds_read_b64_tr_b16 v[64:65], v179 offset:1536
	ds_read_b64_tr_b16 v[66:67], v179 offset:3584
	v_exp_f32_e32 v106, v106
	v_exp_f32_e32 v107, v107
	v_add_f32_e32 v255, v255, v101
	s_waitcnt lgkmcnt(10)
	v_mfma_f32_32x32x16_bf16 v[16:31], v[236:239], v[68:71], v[16:31]
	ds_read_b64_tr_b16 v[68:69], v179 offset:5632
	ds_read_b64_tr_b16 v[70:71], v179 offset:7680
	v_exp_f32_e32 v108, v108
	v_exp_f32_e32 v109, v109
	v_add_f32_e32 v254, v254, v102
	s_waitcnt lgkmcnt(10)
	v_mfma_f32_32x32x16_bf16 v[32:47], v[224:227], v[72:75], v[32:47]
	ds_read_b64_tr_b16 v[72:73], v179 offset:9728
	ds_read_b64_tr_b16 v[74:75], v179 offset:11776
	v_exp_f32_e32 v110, v110
	v_exp_f32_e32 v111, v111
	v_add_f32_e32 v255, v255, v103
	s_waitcnt lgkmcnt(10)
	v_mfma_f32_32x32x16_bf16 v[32:47], v[228:231], v[76:79], v[32:47]
	ds_read_b64_tr_b16 v[76:77], v179 offset:13824
	ds_read_b64_tr_b16 v[78:79], v179 offset:15872
	v_add_f32_e32 v254, v254, v104
	v_add_f32_e32 v255, v255, v105
	v_add_f32_e32 v254, v254, v106
	s_waitcnt lgkmcnt(10)
	v_mfma_f32_32x32x16_bf16 v[32:47], v[232:235], v[240:243], v[32:47]
	v_add_f32_e32 v255, v255, v107
	v_add_f32_e32 v254, v254, v108
	v_add_f32_e32 v255, v255, v109
	s_waitcnt lgkmcnt(8)
	v_mfma_f32_32x32x16_bf16 v[32:47], v[236:239], v[244:247], v[32:47]
	v_add_f32_e32 v254, v254, v110
	v_add_f32_e32 v255, v255, v111
	s_waitcnt vmcnt(0)
	s_waitcnt lgkmcnt(0)
	s_barrier
; #define SBAR() __builtin_amdgcn_sched_barrier(0)
; __device__ __forceinline__ void partialSM_fix(f32x16& p0) { for (int r = 0; r < 16; ++r) p0[r] = __builtin_amdgcn_exp2f(p0[r]); }
; #define SLOAD(i, k0) do { sr_[i].vs0 = St::ld8(&Vh[(long)((k0) + sr) * LDK + sc]); sr_[i].vs1 = St::ld8(&Vh[(long)((k0) + 32 + sr) * LDK + sc]); \
;     sr_[i].ks0 = St::ld8(&Kh[(long)((k0) + sr) * LDK + sc]); sr_[i].ks1 = St::ld8(&Kh[(long)((k0) + 32 + sr) * LDK + sc]); } while (0)
; #define SWAIT() do { if constexpr (SDEPTH == 2) asm volatile("s_waitcnt vmcnt(4)" ::: "memory"); else asm volatile("s_waitcnt vmcnt(0)" ::: "memory"); } while (0)
; template <typename TQ>
; __device__ __forceinline__ void attn_dense_body(const TQ* __restrict__ Qb, const bf16* __restrict__ Kh, const bf16* __restrict__ Vh,
;                                                 bf16* __restrict__ Ob, int seq, char* lds) {
;     ...
;     SBAR(); qkt(pB0, pB1, (bf16*)((char*)K_lds + cur * (int)SHM_K), qr, r32, hi);
;     finishSM(pA0, pA1, alA, l_reg, pa0, pa1, pa2, pa3); SBAR();
;     SWAIT(); SWRITE(next, SE);
;     if (j + 2 < NT) SLOAD(SO, (j + 2) * KVBLK); SBAR();
;     pv_d0(o, vb0 + prev * (int)SHM_V, pa0, pa1, pa2, pa3); partialSM_fix(pB0);
;     __syncthreads();
;     { const int t_ = prev; prev = cur; cur = next; next = t_; }
;     SBAR(); qkt(pA0, pA1, (bf16*)((char*)K_lds + cur * (int)SHM_K), qr, r32, hi);
;     finishSM(pB0, pB1, alB, l_reg, pa0, pa1, pa2, pa3); SBAR();
;     if (j + 2 < NT) { SWAIT(); SWRITE(next, SO); }
;     if (j + 3 < NT) SLOAD(SE, (j + 3) * KVBLK); SBAR();
;     pv_d0(o, vb0 + prev * (int)SHM_V, pa0, pa1, pa2, pa3); partialSM_fix(pA0);
	ds_read_b128 v[208:211], v144 offset:32768
	ds_read_b128 v[212:215], v144 offset:40960
	ds_read_b128 v[216:219], v145 offset:32768
	ds_read_b128 v[220:223], v145 offset:40960
	ds_read_b128 v[240:243], v146 offset:32768
	ds_read_b128 v[244:247], v146 offset:40960
	v_mfma_f32_32x32x16_bf16 v[48:63], v[224:227], v[64:67], v[48:63]
	v_add_f32_e32 v254, v254, v255
	s_add_i32 m0, s80, 0x0
	s_add_u32 s96, s90, 0x80
	s_addc_u32 s97, s91, 0
	global_load_lds_dwordx4 v249, s[90:91]
	v_mfma_f32_32x32x16_bf16 v[48:63], v[228:231], v[68:71], v[48:63]
	s_add_i32 m0, s81, 0x0
	s_nop 0
	global_load_lds_dwordx4 v249, s[96:97]
	v_mfma_f32_32x32x16_bf16 v[48:63], v[232:235], v[72:75], v[48:63]
	s_add_i32 m0, s82, 0x0
	s_nop 0
	global_load_lds_dwordx4 v174, s[92:93]
	v_mfma_f32_32x32x16_bf16 v[48:63], v[236:239], v[76:79], v[48:63]
	s_add_i32 m0, s83, 0x0
	s_add_u32 s90, s90, 0x4000
	global_load_lds_dwordx4 v175, s[92:93]
	s_addc_u32 s91, s91, 0
	s_add_u32 s92, s92, 0x4000
	s_addc_u32 s93, s93, 0
	s_waitcnt lgkmcnt(4)
	v_mfma_f32_32x32x16_bf16 v[224:239], v[208:211], v[140:143], 0
	v_exp_f32_e32 v80, v80
	v_exp_f32_e32 v81, v81
	v_cvt_pk_bf16_f32 v96, v96, v97
	v_mfma_f32_32x32x16_bf16 v[64:79], v[212:215], v[140:143], 0
	ds_read_b128 v[208:211], v147 offset:32768
	ds_read_b128 v[212:215], v147 offset:40960
	v_exp_f32_e32 v82, v82
	v_exp_f32_e32 v83, v83
	v_cvt_pk_bf16_f32 v97, v98, v99
	s_waitcnt lgkmcnt(4)
	v_mfma_f32_32x32x16_bf16 v[224:239], v[216:219], v[136:139], v[224:239]
	v_exp_f32_e32 v84, v84
	v_exp_f32_e32 v85, v85
	v_cvt_pk_bf16_f32 v98, v100, v101
	v_mfma_f32_32x32x16_bf16 v[64:79], v[220:223], v[136:139], v[64:79]
	ds_read_b128 v[216:219], v148 offset:32768
	ds_read_b128 v[220:223], v148 offset:40960
	v_exp_f32_e32 v86, v86
	v_exp_f32_e32 v87, v87
	v_cvt_pk_bf16_f32 v99, v102, v103
	v_add_f32_e32 v251, v80, v82
	s_waitcnt lgkmcnt(4)
	v_mfma_f32_32x32x16_bf16 v[224:239], v[240:243], v[132:135], v[224:239]
	v_exp_f32_e32 v88, v88
	v_exp_f32_e32 v89, v89
	v_add_f32_e32 v253, v81, v83
	v_mfma_f32_32x32x16_bf16 v[64:79], v[244:247], v[132:135], v[64:79]
	ds_read_b128 v[240:243], v149 offset:32768
	ds_read_b128 v[244:247], v149 offset:40960
	v_exp_f32_e32 v90, v90
	v_exp_f32_e32 v91, v91
	v_add_f32_e32 v251, v251, v84
	s_waitcnt lgkmcnt(4)
	v_mfma_f32_32x32x16_bf16 v[224:239], v[208:211], v[128:131], v[224:239]
	v_exp_f32_e32 v92, v92
	v_exp_f32_e32 v93, v93
	v_add_f32_e32 v253, v253, v85
	v_cvt_pk_bf16_f32 v100, v104, v105
	v_mfma_f32_32x32x16_bf16 v[64:79], v[212:215], v[128:131], v[64:79]
	ds_read_b128 v[208:211], v150 offset:32768
	ds_read_b128 v[212:215], v150 offset:40960
	v_exp_f32_e32 v94, v94
	v_exp_f32_e32 v95, v95
	v_add_f32_e32 v251, v251, v86
	v_cvt_pk_bf16_f32 v101, v106, v107
	s_waitcnt lgkmcnt(4)
	v_mfma_f32_32x32x16_bf16 v[224:239], v[216:219], v[124:127], v[224:239]
	v_add_f32_e32 v253, v253, v87
	v_cvt_pk_bf16_f32 v102, v108, v109
	v_cvt_pk_bf16_f32 v103, v110, v111
	v_add_f32_e32 v251, v251, v88
	v_mfma_f32_32x32x16_bf16 v[64:79], v[220:223], v[124:127], v[64:79]
	ds_read_b128 v[216:219], v151 offset:32768
	ds_read_b128 v[220:223], v151 offset:40960
	v_add_f32_e32 v253, v253, v89
	v_cvt_pk_bf16_f32 v104, v80, v81
	v_cvt_pk_bf16_f32 v105, v82, v83
	s_waitcnt lgkmcnt(4)
	v_mfma_f32_32x32x16_bf16 v[224:239], v[240:243], v[120:123], v[224:239]
	v_add_f32_e32 v251, v251, v90
	v_cvt_pk_bf16_f32 v106, v84, v85
	v_cvt_pk_bf16_f32 v107, v86, v87
	v_mfma_f32_32x32x16_bf16 v[64:79], v[244:247], v[120:123], v[64:79]
	ds_read_b64_tr_b16 v[240:241], v179 offset:16384
	ds_read_b64_tr_b16 v[242:243], v179 offset:18432
	ds_read_b64_tr_b16 v[244:245], v179 offset:20480
	ds_read_b64_tr_b16 v[246:247], v179 offset:22528
	v_add_f32_e32 v253, v253, v91
	v_add_f32_e32 v251, v251, v92
	v_cvt_pk_bf16_f32 v108, v88, v89
	v_cvt_pk_bf16_f32 v109, v90, v91
	s_waitcnt lgkmcnt(6)
	v_mfma_f32_32x32x16_bf16 v[224:239], v[208:211], v[116:119], v[224:239]
	v_add_f32_e32 v253, v253, v93
	v_add_f32_e32 v251, v251, v94
	v_mfma_f32_32x32x16_bf16 v[64:79], v[212:215], v[116:119], v[64:79]
	ds_read_b64_tr_b16 v[208:209], v179 offset:24576
	ds_read_b64_tr_b16 v[210:211], v179 offset:26624
	ds_read_b64_tr_b16 v[212:213], v179 offset:28672
	ds_read_b64_tr_b16 v[214:215], v179 offset:30720
	v_add_f32_e32 v253, v253, v95
	v_cvt_pk_bf16_f32 v110, v92, v93
	v_cvt_pk_bf16_f32 v111, v94, v95
	s_waitcnt lgkmcnt(8)
	v_mfma_f32_32x32x16_bf16 v[224:239], v[216:219], v[112:115], v[224:239]
	v_add_f32_e32 v251, v251, v253
	v_add_f32_e32 v254, v254, v251
	v_mfma_f32_32x32x16_bf16 v[64:79], v[220:223], v[112:115], v[64:79]
	ds_read_b64_tr_b16 v[216:217], v179 offset:16896
	ds_read_b64_tr_b16 v[218:219], v179 offset:18944
	ds_read_b64_tr_b16 v[220:221], v179 offset:20992
	ds_read_b64_tr_b16 v[222:223], v179 offset:23040
	v_add_f32_e32 v169, v169, v254
	s_waitcnt lgkmcnt(10)
	v_mfma_f32_32x32x16_bf16 v[0:15], v[96:99], v[240:243], v[0:15]
	ds_read_b64_tr_b16 v[80:81], v179 offset:25088
	ds_read_b64_tr_b16 v[82:83], v179 offset:27136
	s_waitcnt lgkmcnt(10)
	v_mfma_f32_32x32x16_bf16 v[0:15], v[100:103], v[244:247], v[0:15]
	ds_read_b64_tr_b16 v[84:85], v179 offset:29184
	ds_read_b64_tr_b16 v[86:87], v179 offset:31232
	v_exp_f32_e32 v224, v224
	v_exp_f32_e32 v225, v225
	s_waitcnt lgkmcnt(10)
	v_mfma_f32_32x32x16_bf16 v[0:15], v[104:107], v[208:211], v[0:15]
	ds_read_b64_tr_b16 v[88:89], v179 offset:17408
	ds_read_b64_tr_b16 v[90:91], v179 offset:19456
	v_exp_f32_e32 v226, v226
	v_exp_f32_e32 v227, v227
	s_waitcnt lgkmcnt(10)
	v_mfma_f32_32x32x16_bf16 v[0:15], v[108:111], v[212:215], v[0:15]
	ds_read_b64_tr_b16 v[92:93], v179 offset:21504
	ds_read_b64_tr_b16 v[94:95], v179 offset:23552
	v_exp_f32_e32 v228, v228
	v_exp_f32_e32 v229, v229
	v_add_f32_e32 v254, v224, v226
	s_waitcnt lgkmcnt(10)
; #define SBAR() __builtin_amdgcn_sched_barrier(0)
; __device__ __forceinline__ void partialSM_fix(f32x16& p0) { for (int r = 0; r < 16; ++r) p0[r] = __builtin_amdgcn_exp2f(p0[r]); }
; #define SLOAD(i, k0) do { sr_[i].vs0 = St::ld8(&Vh[(long)((k0) + sr) * LDK + sc]); sr_[i].vs1 = St::ld8(&Vh[(long)((k0) + 32 + sr) * LDK + sc]); \
;     sr_[i].ks0 = St::ld8(&Kh[(long)((k0) + sr) * LDK + sc]); sr_[i].ks1 = St::ld8(&Kh[(long)((k0) + 32 + sr) * LDK + sc]); } while (0)
; #define SWAIT() do { if constexpr (SDEPTH == 2) asm volatile("s_waitcnt vmcnt(4)" ::: "memory"); else asm volatile("s_waitcnt vmcnt(0)" ::: "memory"); } while (0)
; template <typename TQ>
; __device__ __forceinline__ void attn_dense_body(const TQ* __restrict__ Qb, const bf16* __restrict__ Kh, const bf16* __restrict__ Vh,
;                                                 bf16* __restrict__ Ob, int seq, char* lds) {
;     ...
;     if (j + 2 < NT) SLOAD(SO, (j + 2) * KVBLK); SBAR();
;     pv_d0(o, vb0 + prev * (int)SHM_V, pa0, pa1, pa2, pa3); partialSM_fix(pB0);
;     __syncthreads();
;     { const int t_ = prev; prev = cur; cur = next; next = t_; }
;     SBAR(); qkt(pA0, pA1, (bf16*)((char*)K_lds + cur * (int)SHM_K), qr, r32, hi);
;     finishSM(pB0, pB1, alB, l_reg, pa0, pa1, pa2, pa3); SBAR();
;     if (j + 2 < NT) { SWAIT(); SWRITE(next, SO); }
;     if (j + 3 < NT) SLOAD(SE, (j + 3) * KVBLK); SBAR();
;     pv_d0(o, vb0 + prev * (int)SHM_V, pa0, pa1, pa2, pa3); partialSM_fix(pA0);
;     __syncthreads();
;     { const int t_ = prev; prev = cur; cur = next; next = t_; }
	v_mfma_f32_32x32x16_bf16 v[16:31], v[96:99], v[216:219], v[16:31]
	ds_read_b64_tr_b16 v[240:241], v179 offset:25600
	ds_read_b64_tr_b16 v[242:243], v179 offset:27648
	v_exp_f32_e32 v230, v230
	v_exp_f32_e32 v231, v231
	v_add_f32_e32 v255, v225, v227
	s_waitcnt lgkmcnt(10)
	v_mfma_f32_32x32x16_bf16 v[16:31], v[100:103], v[220:223], v[16:31]
	ds_read_b64_tr_b16 v[244:245], v179 offset:29696
	ds_read_b64_tr_b16 v[246:247], v179 offset:31744
	v_exp_f32_e32 v232, v232
	v_exp_f32_e32 v233, v233
	v_add_f32_e32 v254, v254, v228
	s_waitcnt lgkmcnt(10)
	v_mfma_f32_32x32x16_bf16 v[16:31], v[104:107], v[80:83], v[16:31]
	ds_read_b64_tr_b16 v[80:81], v179 offset:17920
	ds_read_b64_tr_b16 v[82:83], v179 offset:19968
	v_exp_f32_e32 v234, v234
	v_exp_f32_e32 v235, v235
	v_add_f32_e32 v255, v255, v229
	s_waitcnt lgkmcnt(10)
	v_mfma_f32_32x32x16_bf16 v[16:31], v[108:111], v[84:87], v[16:31]
	ds_read_b64_tr_b16 v[84:85], v179 offset:22016
	ds_read_b64_tr_b16 v[86:87], v179 offset:24064
	v_exp_f32_e32 v236, v236
	v_exp_f32_e32 v237, v237
	v_add_f32_e32 v254, v254, v230
	s_waitcnt lgkmcnt(10)
	v_mfma_f32_32x32x16_bf16 v[32:47], v[96:99], v[88:91], v[32:47]
	ds_read_b64_tr_b16 v[88:89], v179 offset:26112
	ds_read_b64_tr_b16 v[90:91], v179 offset:28160
	v_exp_f32_e32 v238, v238
	v_exp_f32_e32 v239, v239
	v_add_f32_e32 v255, v255, v231
	s_waitcnt lgkmcnt(10)
	v_mfma_f32_32x32x16_bf16 v[32:47], v[100:103], v[92:95], v[32:47]
	ds_read_b64_tr_b16 v[92:93], v179 offset:30208
	ds_read_b64_tr_b16 v[94:95], v179 offset:32256
	v_add_f32_e32 v254, v254, v232
	v_add_f32_e32 v255, v255, v233
	v_add_f32_e32 v254, v254, v234
	s_waitcnt lgkmcnt(10)
	v_mfma_f32_32x32x16_bf16 v[32:47], v[104:107], v[240:243], v[32:47]
	v_add_f32_e32 v255, v255, v235
	v_add_f32_e32 v254, v254, v236
	v_add_f32_e32 v255, v255, v237
	s_waitcnt lgkmcnt(8)
	v_mfma_f32_32x32x16_bf16 v[32:47], v[108:111], v[244:247], v[32:47]
	v_add_f32_e32 v254, v254, v238
	v_add_f32_e32 v255, v255, v239
	s_waitcnt vmcnt(0)
	s_waitcnt lgkmcnt(0)
	s_barrier
	ds_read_b128 v[208:211], v144 offset:0
	ds_read_b128 v[212:215], v144 offset:8192
	ds_read_b128 v[216:219], v145 offset:0
	ds_read_b128 v[220:223], v145 offset:8192
	ds_read_b128 v[240:243], v146 offset:0
	ds_read_b128 v[244:247], v146 offset:8192
	v_mfma_f32_32x32x16_bf16 v[48:63], v[96:99], v[80:83], v[48:63]
	v_add_f32_e32 v254, v254, v255
	s_cmp_ge_u32 s55, s53
	s_cbranch_scc1 .Latt_nodma0_i0
	s_add_i32 m0, s80, 0x4000
	s_add_u32 s96, s90, 0x80
	s_addc_u32 s97, s91, 0
	global_load_lds_dwordx4 v249, s[90:91]
.Latt_nodma0_i0:
	v_mfma_f32_32x32x16_bf16 v[48:63], v[100:103], v[84:87], v[48:63]
	s_cmp_ge_u32 s55, s53
	s_cbranch_scc1 .Latt_nodma1_i0
	s_add_i32 m0, s81, 0x4000
	s_nop 0
	global_load_lds_dwordx4 v249, s[96:97]
.Latt_nodma1_i0:
	v_mfma_f32_32x32x16_bf16 v[48:63], v[104:107], v[88:91], v[48:63]
	s_cmp_ge_u32 s55, s53
	s_cbranch_scc1 .Latt_nodma2_i0
	s_add_i32 m0, s82, 0x4000
	s_nop 0
	global_load_lds_dwordx4 v174, s[92:93]
.Latt_nodma2_i0:
	v_mfma_f32_32x32x16_bf16 v[48:63], v[108:111], v[92:95], v[48:63]
	s_cmp_ge_u32 s55, s53
	s_cbranch_scc1 .Latt_nodma3_i0
	s_add_i32 m0, s83, 0x4000
	s_add_u32 s90, s90, 0x4000
	global_load_lds_dwordx4 v175, s[92:93]
	s_addc_u32 s91, s91, 0
	s_add_u32 s92, s92, 0x4000
	s_addc_u32 s93, s93, 0
.Latt_nodma3_i0:
	s_add_i32 s55, s55, 2
	s_cmp_ge_u32 s55, s32
	s_cbranch_scc1 .Latt_exit_0
	s_waitcnt lgkmcnt(4)
	v_mfma_f32_32x32x16_bf16 v[96:111], v[208:211], v[140:143], 0
	v_exp_f32_e32 v64, v64
	v_exp_f32_e32 v65, v65
	v_cvt_pk_bf16_f32 v224, v224, v225
	v_mfma_f32_32x32x16_bf16 v[80:95], v[212:215], v[140:143], 0
	ds_read_b128 v[208:211], v147 offset:0
	ds_read_b128 v[212:215], v147 offset:8192
	v_exp_f32_e32 v66, v66
	v_exp_f32_e32 v67, v67
	v_cvt_pk_bf16_f32 v225, v226, v227
	s_waitcnt lgkmcnt(4)
	v_mfma_f32_32x32x16_bf16 v[96:111], v[216:219], v[136:139], v[96:111]
	v_exp_f32_e32 v68, v68
	v_exp_f32_e32 v69, v69
	v_cvt_pk_bf16_f32 v226, v228, v229
	v_mfma_f32_32x32x16_bf16 v[80:95], v[220:223], v[136:139], v[80:95]
	ds_read_b128 v[216:219], v148 offset:0
	ds_read_b128 v[220:223], v148 offset:8192
	v_exp_f32_e32 v70, v70
	v_exp_f32_e32 v71, v71
	v_cvt_pk_bf16_f32 v227, v230, v231
	v_add_f32_e32 v251, v64, v66
	s_waitcnt lgkmcnt(4)
	v_mfma_f32_32x32x16_bf16 v[96:111], v[240:243], v[132:135], v[96:111]
	v_exp_f32_e32 v72, v72
	v_exp_f32_e32 v73, v73
	v_add_f32_e32 v253, v65, v67
	v_mfma_f32_32x32x16_bf16 v[80:95], v[244:247], v[132:135], v[80:95]
	ds_read_b128 v[240:243], v149 offset:0
	ds_read_b128 v[244:247], v149 offset:8192
	v_exp_f32_e32 v74, v74
	v_exp_f32_e32 v75, v75
	v_add_f32_e32 v251, v251, v68
	s_waitcnt lgkmcnt(4)
	v_mfma_f32_32x32x16_bf16 v[96:111], v[208:211], v[128:131], v[96:111]
	v_exp_f32_e32 v76, v76
	v_exp_f32_e32 v77, v77
	v_add_f32_e32 v253, v253, v69
	v_cvt_pk_bf16_f32 v228, v232, v233
	v_mfma_f32_32x32x16_bf16 v[80:95], v[212:215], v[128:131], v[80:95]
	ds_read_b128 v[208:211], v150 offset:0
	ds_read_b128 v[212:215], v150 offset:8192
	v_exp_f32_e32 v78, v78
	v_exp_f32_e32 v79, v79
	v_add_f32_e32 v251, v251, v70
	v_cvt_pk_bf16_f32 v229, v234, v235
	s_waitcnt lgkmcnt(4)
	v_mfma_f32_32x32x16_bf16 v[96:111], v[216:219], v[124:127], v[96:111]
	v_add_f32_e32 v253, v253, v71
	v_cvt_pk_bf16_f32 v230, v236, v237
	v_cvt_pk_bf16_f32 v231, v238, v239
	v_add_f32_e32 v251, v251, v72
	v_mfma_f32_32x32x16_bf16 v[80:95], v[220:223], v[124:127], v[80:95]
	ds_read_b128 v[216:219], v151 offset:0
	ds_read_b128 v[220:223], v151 offset:8192
	v_add_f32_e32 v253, v253, v73
	v_cvt_pk_bf16_f32 v232, v64, v65
	v_cvt_pk_bf16_f32 v233, v66, v67
	s_waitcnt lgkmcnt(4)
; #define SBAR() __builtin_amdgcn_sched_barrier(0)
; __device__ __forceinline__ void partialSM_fix(f32x16& p0) { for (int r = 0; r < 16; ++r) p0[r] = __builtin_amdgcn_exp2f(p0[r]); }
; #define SLOAD(i, k0) do { sr_[i].vs0 = St::ld8(&Vh[(long)((k0) + sr) * LDK + sc]); sr_[i].vs1 = St::ld8(&Vh[(long)((k0) + 32 + sr) * LDK + sc]); \
;     sr_[i].ks0 = St::ld8(&Kh[(long)((k0) + sr) * LDK + sc]); sr_[i].ks1 = St::ld8(&Kh[(long)((k0) + 32 + sr) * LDK + sc]); } while (0)
; #define SWAIT() do { if constexpr (SDEPTH == 2) asm volatile("s_waitcnt vmcnt(4)" ::: "memory"); else asm volatile("s_waitcnt vmcnt(0)" ::: "memory"); } while (0)
; template <int D0> __device__ __forceinline__ void pv_one(f32x16& od, int vb, bf16x8 pa0, bf16x8 pa1, bf16x8 pa2, bf16x8 pa3) {
;   const s16x4 l0 = tr_read<v_rd_off(D0, 0, 0)>(vb), h0 = tr_read<v_rd_off(D0, 0, 1)>(vb), l1 = tr_read<v_rd_off(D0, 1, 0)>(vb), h1 = tr_read<v_rd_off(D0, 1, 1)>(vb);
;   const s16x4 l2 = tr_read<v_rd_off(D0, 2, 0)>(vb), h2 = tr_read<v_rd_off(D0, 2, 1)>(vb), l3 = tr_read<v_rd_off(D0, 3, 0)>(vb), h3 = tr_read<v_rd_off(D0, 3, 1)>(vb);
;   asm volatile("s_waitcnt lgkmcnt(0)" ::: "memory"); SBAR();
;     ...
;   od = __builtin_amdgcn_mfma_f32_32x32x16_bf16(pa0, PK(l0, h0), od, 0, 0, 0);
;   od = __builtin_amdgcn_mfma_f32_32x32x16_bf16(pa1, PK(l1, h1), od, 0, 0, 0);
;   od = __builtin_amdgcn_mfma_f32_32x32x16_bf16(pa2, PK(l2, h2), od, 0, 0, 0);
;   od = __builtin_amdgcn_mfma_f32_32x32x16_bf16(pa3, PK(l3, h3), od, 0, 0, 0);
;     ...
; }
; __device__ __forceinline__ void pv_d0(f32x16* o, int vb, bf16x8 pa0, bf16x8 pa1, bf16x8 pa2, bf16x8 pa3) {
;   pv_one<0>(o[0], vb, pa0, pa1, pa2, pa3); pv_one<1>(o[1], vb, pa0, pa1, pa2, pa3); pv_one<2>(o[2], vb, pa0, pa1, pa2, pa3); pv_one<3>(o[3], vb, pa0, pa1, pa2, pa3);
; }
; template <typename TQ>
; __device__ __forceinline__ void attn_dense_body(const TQ* __restrict__ Qb, const bf16* __restrict__ Kh, const bf16* __restrict__ Vh,
;                                                 bf16* __restrict__ Ob, int seq, char* lds) {
;     ...
;     SBAR(); qkt(pB0, pB1, (bf16*)((char*)K_lds + cur * (int)SHM_K), qr, r32, hi);
;     finishSM(pA0, pA1, alA, l_reg, pa0, pa1, pa2, pa3); SBAR();
;     SWAIT(); SWRITE(next, SE);
;     if (j + 2 < NT) SLOAD(SO, (j + 2) * KVBLK); SBAR();
;     pv_d0(o, vb0 + prev * (int)SHM_V, pa0, pa1, pa2, pa3); partialSM_fix(pB0);
;     __syncthreads();
	v_mfma_f32_32x32x16_bf16 v[96:111], v[240:243], v[120:123], v[96:111]
	v_add_f32_e32 v251, v251, v74
	v_cvt_pk_bf16_f32 v234, v68, v69
	v_cvt_pk_bf16_f32 v235, v70, v71
	v_mfma_f32_32x32x16_bf16 v[80:95], v[244:247], v[120:123], v[80:95]
	ds_read_b64_tr_b16 v[240:241], v179 offset:32768
	ds_read_b64_tr_b16 v[242:243], v179 offset:34816
	ds_read_b64_tr_b16 v[244:245], v179 offset:36864
	ds_read_b64_tr_b16 v[246:247], v179 offset:38912
	v_add_f32_e32 v253, v253, v75
	v_add_f32_e32 v251, v251, v76
	v_cvt_pk_bf16_f32 v236, v72, v73
	v_cvt_pk_bf16_f32 v237, v74, v75
	s_waitcnt lgkmcnt(6)
	v_mfma_f32_32x32x16_bf16 v[96:111], v[208:211], v[116:119], v[96:111]
	v_add_f32_e32 v253, v253, v77
	v_add_f32_e32 v251, v251, v78
	v_mfma_f32_32x32x16_bf16 v[80:95], v[212:215], v[116:119], v[80:95]
	ds_read_b64_tr_b16 v[208:209], v179 offset:40960
	ds_read_b64_tr_b16 v[210:211], v179 offset:43008
	ds_read_b64_tr_b16 v[212:213], v179 offset:45056
	ds_read_b64_tr_b16 v[214:215], v179 offset:47104
	v_add_f32_e32 v253, v253, v79
	v_cvt_pk_bf16_f32 v238, v76, v77
	v_cvt_pk_bf16_f32 v239, v78, v79
	s_waitcnt lgkmcnt(8)
	v_mfma_f32_32x32x16_bf16 v[96:111], v[216:219], v[112:115], v[96:111]
	v_add_f32_e32 v251, v251, v253
	v_add_f32_e32 v254, v254, v251
	v_mfma_f32_32x32x16_bf16 v[80:95], v[220:223], v[112:115], v[80:95]
	ds_read_b64_tr_b16 v[216:217], v179 offset:33280
	ds_read_b64_tr_b16 v[218:219], v179 offset:35328
	ds_read_b64_tr_b16 v[220:221], v179 offset:37376
	ds_read_b64_tr_b16 v[222:223], v179 offset:39424
	v_add_f32_e32 v169, v169, v254
	s_waitcnt lgkmcnt(10)
	v_mfma_f32_32x32x16_bf16 v[0:15], v[224:227], v[240:243], v[0:15]
	ds_read_b64_tr_b16 v[64:65], v179 offset:41472
	ds_read_b64_tr_b16 v[66:67], v179 offset:43520
	s_waitcnt lgkmcnt(10)
	v_mfma_f32_32x32x16_bf16 v[0:15], v[228:231], v[244:247], v[0:15]
	ds_read_b64_tr_b16 v[68:69], v179 offset:45568
	ds_read_b64_tr_b16 v[70:71], v179 offset:47616
	v_exp_f32_e32 v96, v96
	v_exp_f32_e32 v97, v97
	s_waitcnt lgkmcnt(10)
	v_mfma_f32_32x32x16_bf16 v[0:15], v[232:235], v[208:211], v[0:15]
	ds_read_b64_tr_b16 v[72:73], v179 offset:33792
	ds_read_b64_tr_b16 v[74:75], v179 offset:35840
	v_exp_f32_e32 v98, v98
	v_exp_f32_e32 v99, v99
	s_waitcnt lgkmcnt(10)
	v_mfma_f32_32x32x16_bf16 v[0:15], v[236:239], v[212:215], v[0:15]
	ds_read_b64_tr_b16 v[76:77], v179 offset:37888
	ds_read_b64_tr_b16 v[78:79], v179 offset:39936
	v_exp_f32_e32 v100, v100
	v_exp_f32_e32 v101, v101
	v_add_f32_e32 v254, v96, v98
	s_waitcnt lgkmcnt(10)
	v_mfma_f32_32x32x16_bf16 v[16:31], v[224:227], v[216:219], v[16:31]
	ds_read_b64_tr_b16 v[240:241], v179 offset:41984
	ds_read_b64_tr_b16 v[242:243], v179 offset:44032
	v_exp_f32_e32 v102, v102
	v_exp_f32_e32 v103, v103
	v_add_f32_e32 v255, v97, v99
	s_waitcnt lgkmcnt(10)
	v_mfma_f32_32x32x16_bf16 v[16:31], v[228:231], v[220:223], v[16:31]
	ds_read_b64_tr_b16 v[244:245], v179 offset:46080
	ds_read_b64_tr_b16 v[246:247], v179 offset:48128
	v_exp_f32_e32 v104, v104
	v_exp_f32_e32 v105, v105
	v_add_f32_e32 v254, v254, v100
	s_waitcnt lgkmcnt(10)
	v_mfma_f32_32x32x16_bf16 v[16:31], v[232:235], v[64:67], v[16:31]
	ds_read_b64_tr_b16 v[64:65], v179 offset:34304
	ds_read_b64_tr_b16 v[66:67], v179 offset:36352
	v_exp_f32_e32 v106, v106
	v_exp_f32_e32 v107, v107
	v_add_f32_e32 v255, v255, v101
	s_waitcnt lgkmcnt(10)
	v_mfma_f32_32x32x16_bf16 v[16:31], v[236:239], v[68:71], v[16:31]
	ds_read_b64_tr_b16 v[68:69], v179 offset:38400
	ds_read_b64_tr_b16 v[70:71], v179 offset:40448
	v_exp_f32_e32 v108, v108
	v_exp_f32_e32 v109, v109
	v_add_f32_e32 v254, v254, v102
	s_waitcnt lgkmcnt(10)
	v_mfma_f32_32x32x16_bf16 v[32:47], v[224:227], v[72:75], v[32:47]
	ds_read_b64_tr_b16 v[72:73], v179 offset:42496
	ds_read_b64_tr_b16 v[74:75], v179 offset:44544
	v_exp_f32_e32 v110, v110
	v_exp_f32_e32 v111, v111
	v_add_f32_e32 v255, v255, v103
	s_waitcnt lgkmcnt(10)
	v_mfma_f32_32x32x16_bf16 v[32:47], v[228:231], v[76:79], v[32:47]
	ds_read_b64_tr_b16 v[76:77], v179 offset:46592
	ds_read_b64_tr_b16 v[78:79], v179 offset:48640
	v_add_f32_e32 v254, v254, v104
	v_add_f32_e32 v255, v255, v105
	v_add_f32_e32 v254, v254, v106
	s_waitcnt lgkmcnt(10)
	v_mfma_f32_32x32x16_bf16 v[32:47], v[232:235], v[240:243], v[32:47]
	v_add_f32_e32 v255, v255, v107
	v_add_f32_e32 v254, v254, v108
	v_add_f32_e32 v255, v255, v109
	s_waitcnt lgkmcnt(8)
	v_mfma_f32_32x32x16_bf16 v[32:47], v[236:239], v[244:247], v[32:47]
	v_add_f32_e32 v254, v254, v110
	v_add_f32_e32 v255, v255, v111
	s_waitcnt vmcnt(0)
	s_waitcnt lgkmcnt(0)
	s_barrier
; #define SBAR() __builtin_amdgcn_sched_barrier(0)
; __device__ __forceinline__ void partialSM_fix(f32x16& p0) { for (int r = 0; r < 16; ++r) p0[r] = __builtin_amdgcn_exp2f(p0[r]); }
; #define SLOAD(i, k0) do { sr_[i].vs0 = St::ld8(&Vh[(long)((k0) + sr) * LDK + sc]); sr_[i].vs1 = St::ld8(&Vh[(long)((k0) + 32 + sr) * LDK + sc]); \
;     sr_[i].ks0 = St::ld8(&Kh[(long)((k0) + sr) * LDK + sc]); sr_[i].ks1 = St::ld8(&Kh[(long)((k0) + 32 + sr) * LDK + sc]); } while (0)
; #define SWAIT() do { if constexpr (SDEPTH == 2) asm volatile("s_waitcnt vmcnt(4)" ::: "memory"); else asm volatile("s_waitcnt vmcnt(0)" ::: "memory"); } while (0)
; template <typename TQ>
; __device__ __forceinline__ void attn_dense_body(const TQ* __restrict__ Qb, const bf16* __restrict__ Kh, const bf16* __restrict__ Vh,
;                                                 bf16* __restrict__ Ob, int seq, char* lds) {
;     ...
;     SBAR(); qkt(pA0, pA1, (bf16*)((char*)K_lds + cur * (int)SHM_K), qr, r32, hi);
;     finishSM(pB0, pB1, alB, l_reg, pa0, pa1, pa2, pa3); SBAR();
;     if (j + 2 < NT) { SWAIT(); SWRITE(next, SO); }
;     if (j + 3 < NT) SLOAD(SE, (j + 3) * KVBLK); SBAR();
;     pv_d0(o, vb0 + prev * (int)SHM_V, pa0, pa1, pa2, pa3); partialSM_fix(pA0);
	ds_read_b128 v[208:211], v144 offset:16384
	ds_read_b128 v[212:215], v144 offset:24576
	ds_read_b128 v[216:219], v145 offset:16384
	ds_read_b128 v[220:223], v145 offset:24576
	ds_read_b128 v[240:243], v146 offset:16384
	ds_read_b128 v[244:247], v146 offset:24576
	v_mfma_f32_32x32x16_bf16 v[48:63], v[224:227], v[64:67], v[48:63]
	v_add_f32_e32 v254, v254, v255
	s_add_i32 m0, s80, 0x8000
	s_add_u32 s96, s90, 0x80
	s_addc_u32 s97, s91, 0
	global_load_lds_dwordx4 v249, s[90:91]
	v_mfma_f32_32x32x16_bf16 v[48:63], v[228:231], v[68:71], v[48:63]
	s_add_i32 m0, s81, 0x8000
	s_nop 0
	global_load_lds_dwordx4 v249, s[96:97]
	v_mfma_f32_32x32x16_bf16 v[48:63], v[232:235], v[72:75], v[48:63]
	s_add_i32 m0, s82, 0x8000
	s_nop 0
	global_load_lds_dwordx4 v174, s[92:93]
	v_mfma_f32_32x32x16_bf16 v[48:63], v[236:239], v[76:79], v[48:63]
	s_add_i32 m0, s83, 0x8000
	s_add_u32 s90, s90, 0x4000
	global_load_lds_dwordx4 v175, s[92:93]
	s_addc_u32 s91, s91, 0
	s_add_u32 s92, s92, 0x4000
	s_addc_u32 s93, s93, 0
	s_waitcnt lgkmcnt(4)
	v_mfma_f32_32x32x16_bf16 v[224:239], v[208:211], v[140:143], 0
	v_exp_f32_e32 v80, v80
	v_exp_f32_e32 v81, v81
	v_cvt_pk_bf16_f32 v96, v96, v97
	v_mfma_f32_32x32x16_bf16 v[64:79], v[212:215], v[140:143], 0
	ds_read_b128 v[208:211], v147 offset:16384
	ds_read_b128 v[212:215], v147 offset:24576
	v_exp_f32_e32 v82, v82
	v_exp_f32_e32 v83, v83
	v_cvt_pk_bf16_f32 v97, v98, v99
	s_waitcnt lgkmcnt(4)
	v_mfma_f32_32x32x16_bf16 v[224:239], v[216:219], v[136:139], v[224:239]
	v_exp_f32_e32 v84, v84
	v_exp_f32_e32 v85, v85
	v_cvt_pk_bf16_f32 v98, v100, v101
	v_mfma_f32_32x32x16_bf16 v[64:79], v[220:223], v[136:139], v[64:79]
	ds_read_b128 v[216:219], v148 offset:16384
	ds_read_b128 v[220:223], v148 offset:24576
	v_exp_f32_e32 v86, v86
	v_exp_f32_e32 v87, v87
	v_cvt_pk_bf16_f32 v99, v102, v103
	v_add_f32_e32 v251, v80, v82
	s_waitcnt lgkmcnt(4)
	v_mfma_f32_32x32x16_bf16 v[224:239], v[240:243], v[132:135], v[224:239]
	v_exp_f32_e32 v88, v88
	v_exp_f32_e32 v89, v89
	v_add_f32_e32 v253, v81, v83
	v_mfma_f32_32x32x16_bf16 v[64:79], v[244:247], v[132:135], v[64:79]
	ds_read_b128 v[240:243], v149 offset:16384
	ds_read_b128 v[244:247], v149 offset:24576
	v_exp_f32_e32 v90, v90
	v_exp_f32_e32 v91, v91
	v_add_f32_e32 v251, v251, v84
	s_waitcnt lgkmcnt(4)
	v_mfma_f32_32x32x16_bf16 v[224:239], v[208:211], v[128:131], v[224:239]
	v_exp_f32_e32 v92, v92
	v_exp_f32_e32 v93, v93
	v_add_f32_e32 v253, v253, v85
	v_cvt_pk_bf16_f32 v100, v104, v105
	v_mfma_f32_32x32x16_bf16 v[64:79], v[212:215], v[128:131], v[64:79]
	ds_read_b128 v[208:211], v150 offset:16384
	ds_read_b128 v[212:215], v150 offset:24576
	v_exp_f32_e32 v94, v94
	v_exp_f32_e32 v95, v95
	v_add_f32_e32 v251, v251, v86
	v_cvt_pk_bf16_f32 v101, v106, v107
	s_waitcnt lgkmcnt(4)
	v_mfma_f32_32x32x16_bf16 v[224:239], v[216:219], v[124:127], v[224:239]
	v_add_f32_e32 v253, v253, v87
	v_cvt_pk_bf16_f32 v102, v108, v109
	v_cvt_pk_bf16_f32 v103, v110, v111
	v_add_f32_e32 v251, v251, v88
	v_mfma_f32_32x32x16_bf16 v[64:79], v[220:223], v[124:127], v[64:79]
	ds_read_b128 v[216:219], v151 offset:16384
	ds_read_b128 v[220:223], v151 offset:24576
	v_add_f32_e32 v253, v253, v89
	v_cvt_pk_bf16_f32 v104, v80, v81
	v_cvt_pk_bf16_f32 v105, v82, v83
	s_waitcnt lgkmcnt(4)
	v_mfma_f32_32x32x16_bf16 v[224:239], v[240:243], v[120:123], v[224:239]
	v_add_f32_e32 v251, v251, v90
	v_cvt_pk_bf16_f32 v106, v84, v85
	v_cvt_pk_bf16_f32 v107, v86, v87
	v_mfma_f32_32x32x16_bf16 v[64:79], v[244:247], v[120:123], v[64:79]
	ds_read_b64_tr_b16 v[240:241], v179 offset:0
	ds_read_b64_tr_b16 v[242:243], v179 offset:2048
	ds_read_b64_tr_b16 v[244:245], v179 offset:4096
	ds_read_b64_tr_b16 v[246:247], v179 offset:6144
	v_add_f32_e32 v253, v253, v91
	v_add_f32_e32 v251, v251, v92
	v_cvt_pk_bf16_f32 v108, v88, v89
	v_cvt_pk_bf16_f32 v109, v90, v91
	s_waitcnt lgkmcnt(6)
	v_mfma_f32_32x32x16_bf16 v[224:239], v[208:211], v[116:119], v[224:239]
	v_add_f32_e32 v253, v253, v93
	v_add_f32_e32 v251, v251, v94
	v_mfma_f32_32x32x16_bf16 v[64:79], v[212:215], v[116:119], v[64:79]
	ds_read_b64_tr_b16 v[208:209], v179 offset:8192
	ds_read_b64_tr_b16 v[210:211], v179 offset:10240
	ds_read_b64_tr_b16 v[212:213], v179 offset:12288
	ds_read_b64_tr_b16 v[214:215], v179 offset:14336
	v_add_f32_e32 v253, v253, v95
	v_cvt_pk_bf16_f32 v110, v92, v93
	v_cvt_pk_bf16_f32 v111, v94, v95
	s_waitcnt lgkmcnt(8)
	v_mfma_f32_32x32x16_bf16 v[224:239], v[216:219], v[112:115], v[224:239]
	v_add_f32_e32 v251, v251, v253
	v_add_f32_e32 v254, v254, v251
	v_mfma_f32_32x32x16_bf16 v[64:79], v[220:223], v[112:115], v[64:79]
	ds_read_b64_tr_b16 v[216:217], v179 offset:512
	ds_read_b64_tr_b16 v[218:219], v179 offset:2560
	ds_read_b64_tr_b16 v[220:221], v179 offset:4608
	ds_read_b64_tr_b16 v[222:223], v179 offset:6656
	v_add_f32_e32 v169, v169, v254
	s_waitcnt lgkmcnt(10)
	v_mfma_f32_32x32x16_bf16 v[0:15], v[96:99], v[240:243], v[0:15]
	ds_read_b64_tr_b16 v[80:81], v179 offset:8704
	ds_read_b64_tr_b16 v[82:83], v179 offset:10752
	s_waitcnt lgkmcnt(10)
	v_mfma_f32_32x32x16_bf16 v[0:15], v[100:103], v[244:247], v[0:15]
	ds_read_b64_tr_b16 v[84:85], v179 offset:12800
	ds_read_b64_tr_b16 v[86:87], v179 offset:14848
	v_exp_f32_e32 v224, v224
	v_exp_f32_e32 v225, v225
	s_waitcnt lgkmcnt(10)
	v_mfma_f32_32x32x16_bf16 v[0:15], v[104:107], v[208:211], v[0:15]
	ds_read_b64_tr_b16 v[88:89], v179 offset:1024
	ds_read_b64_tr_b16 v[90:91], v179 offset:3072
	v_exp_f32_e32 v226, v226
	v_exp_f32_e32 v227, v227
	s_waitcnt lgkmcnt(10)
	v_mfma_f32_32x32x16_bf16 v[0:15], v[108:111], v[212:215], v[0:15]
	ds_read_b64_tr_b16 v[92:93], v179 offset:5120
	ds_read_b64_tr_b16 v[94:95], v179 offset:7168
	v_exp_f32_e32 v228, v228
	v_exp_f32_e32 v229, v229
	v_add_f32_e32 v254, v224, v226
	s_waitcnt lgkmcnt(10)
; #define SBAR() __builtin_amdgcn_sched_barrier(0)
; __device__ __forceinline__ void partialSM_fix(f32x16& p0) { for (int r = 0; r < 16; ++r) p0[r] = __builtin_amdgcn_exp2f(p0[r]); }
; #define SLOAD(i, k0) do { sr_[i].vs0 = St::ld8(&Vh[(long)((k0) + sr) * LDK + sc]); sr_[i].vs1 = St::ld8(&Vh[(long)((k0) + 32 + sr) * LDK + sc]); \
;     sr_[i].ks0 = St::ld8(&Kh[(long)((k0) + sr) * LDK + sc]); sr_[i].ks1 = St::ld8(&Kh[(long)((k0) + 32 + sr) * LDK + sc]); } while (0)
; #define SWAIT() do { if constexpr (SDEPTH == 2) asm volatile("s_waitcnt vmcnt(4)" ::: "memory"); else asm volatile("s_waitcnt vmcnt(0)" ::: "memory"); } while (0)
; template <typename TQ>
; __device__ __forceinline__ void attn_dense_body(const TQ* __restrict__ Qb, const bf16* __restrict__ Kh, const bf16* __restrict__ Vh,
;                                                 bf16* __restrict__ Ob, int seq, char* lds) {
;     ...
;     SBAR(); qkt(pB0, pB1, (bf16*)((char*)K_lds + cur * (int)SHM_K), qr, r32, hi);
;     finishSM(pA0, pA1, alA, l_reg, pa0, pa1, pa2, pa3); SBAR();
;     SWAIT(); SWRITE(next, SE);
;     ...
;     SBAR(); qkt(pA0, pA1, (bf16*)((char*)K_lds + cur * (int)SHM_K), qr, r32, hi);
;     finishSM(pB0, pB1, alB, l_reg, pa0, pa1, pa2, pa3); SBAR();
;     if (j + 2 < NT) { SWAIT(); SWRITE(next, SO); }
;     if (j + 3 < NT) SLOAD(SE, (j + 3) * KVBLK); SBAR();
;     pv_d0(o, vb0 + prev * (int)SHM_V, pa0, pa1, pa2, pa3); partialSM_fix(pA0);
;     __syncthreads();
;     { const int t_ = prev; prev = cur; cur = next; next = t_; }
	v_mfma_f32_32x32x16_bf16 v[16:31], v[96:99], v[216:219], v[16:31]
	ds_read_b64_tr_b16 v[240:241], v179 offset:9216
	ds_read_b64_tr_b16 v[242:243], v179 offset:11264
	v_exp_f32_e32 v230, v230
	v_exp_f32_e32 v231, v231
	v_add_f32_e32 v255, v225, v227
	s_waitcnt lgkmcnt(10)
	v_mfma_f32_32x32x16_bf16 v[16:31], v[100:103], v[220:223], v[16:31]
	ds_read_b64_tr_b16 v[244:245], v179 offset:13312
	ds_read_b64_tr_b16 v[246:247], v179 offset:15360
	v_exp_f32_e32 v232, v232
	v_exp_f32_e32 v233, v233
	v_add_f32_e32 v254, v254, v228
	s_waitcnt lgkmcnt(10)
	v_mfma_f32_32x32x16_bf16 v[16:31], v[104:107], v[80:83], v[16:31]
	ds_read_b64_tr_b16 v[80:81], v179 offset:1536
	ds_read_b64_tr_b16 v[82:83], v179 offset:3584
	v_exp_f32_e32 v234, v234
	v_exp_f32_e32 v235, v235
	v_add_f32_e32 v255, v255, v229
	s_waitcnt lgkmcnt(10)
	v_mfma_f32_32x32x16_bf16 v[16:31], v[108:111], v[84:87], v[16:31]
	ds_read_b64_tr_b16 v[84:85], v179 offset:5632
	ds_read_b64_tr_b16 v[86:87], v179 offset:7680
	v_exp_f32_e32 v236, v236
	v_exp_f32_e32 v237, v237
	v_add_f32_e32 v254, v254, v230
	s_waitcnt lgkmcnt(10)
	v_mfma_f32_32x32x16_bf16 v[32:47], v[96:99], v[88:91], v[32:47]
	ds_read_b64_tr_b16 v[88:89], v179 offset:9728
	ds_read_b64_tr_b16 v[90:91], v179 offset:11776
	v_exp_f32_e32 v238, v238
	v_exp_f32_e32 v239, v239
	v_add_f32_e32 v255, v255, v231
	s_waitcnt lgkmcnt(10)
	v_mfma_f32_32x32x16_bf16 v[32:47], v[100:103], v[92:95], v[32:47]
	ds_read_b64_tr_b16 v[92:93], v179 offset:13824
	ds_read_b64_tr_b16 v[94:95], v179 offset:15872
	v_add_f32_e32 v254, v254, v232
	v_add_f32_e32 v255, v255, v233
	v_add_f32_e32 v254, v254, v234
	s_waitcnt lgkmcnt(10)
	v_mfma_f32_32x32x16_bf16 v[32:47], v[104:107], v[240:243], v[32:47]
	v_add_f32_e32 v255, v255, v235
	v_add_f32_e32 v254, v254, v236
	v_add_f32_e32 v255, v255, v237
	s_waitcnt lgkmcnt(8)
	v_mfma_f32_32x32x16_bf16 v[32:47], v[108:111], v[244:247], v[32:47]
	v_add_f32_e32 v254, v254, v238
	v_add_f32_e32 v255, v255, v239
	s_waitcnt vmcnt(0)
	s_waitcnt lgkmcnt(0)
	s_barrier
	ds_read_b128 v[208:211], v144 offset:32768
	ds_read_b128 v[212:215], v144 offset:40960
	ds_read_b128 v[216:219], v145 offset:32768
	ds_read_b128 v[220:223], v145 offset:40960
	ds_read_b128 v[240:243], v146 offset:32768
	ds_read_b128 v[244:247], v146 offset:40960
	v_mfma_f32_32x32x16_bf16 v[48:63], v[96:99], v[80:83], v[48:63]
	v_add_f32_e32 v254, v254, v255
	s_cmp_ge_u32 s55, s53
	s_cbranch_scc1 .Latt_nodma0_i1
	s_add_i32 m0, s80, 0x0
	s_add_u32 s96, s90, 0x80
	s_addc_u32 s97, s91, 0
	global_load_lds_dwordx4 v249, s[90:91]
.Latt_nodma0_i1:
	v_mfma_f32_32x32x16_bf16 v[48:63], v[100:103], v[84:87], v[48:63]
	s_cmp_ge_u32 s55, s53
	s_cbranch_scc1 .Latt_nodma1_i1
	s_add_i32 m0, s81, 0x0
	s_nop 0
	global_load_lds_dwordx4 v249, s[96:97]
.Latt_nodma1_i1:
	v_mfma_f32_32x32x16_bf16 v[48:63], v[104:107], v[88:91], v[48:63]
	s_cmp_ge_u32 s55, s53
	s_cbranch_scc1 .Latt_nodma2_i1
	s_add_i32 m0, s82, 0x0
	s_nop 0
	global_load_lds_dwordx4 v174, s[92:93]
.Latt_nodma2_i1:
	v_mfma_f32_32x32x16_bf16 v[48:63], v[108:111], v[92:95], v[48:63]
	s_cmp_ge_u32 s55, s53
	s_cbranch_scc1 .Latt_nodma3_i1
	s_add_i32 m0, s83, 0x0
	s_add_u32 s90, s90, 0x4000
	global_load_lds_dwordx4 v175, s[92:93]
	s_addc_u32 s91, s91, 0
	s_add_u32 s92, s92, 0x4000
	s_addc_u32 s93, s93, 0
.Latt_nodma3_i1:
	s_add_i32 s55, s55, 2
	s_cmp_ge_u32 s55, s32
	s_cbranch_scc1 .Latt_exit_1
	s_waitcnt lgkmcnt(4)
	v_mfma_f32_32x32x16_bf16 v[96:111], v[208:211], v[140:143], 0
	v_exp_f32_e32 v64, v64
	v_exp_f32_e32 v65, v65
	v_cvt_pk_bf16_f32 v224, v224, v225
	v_mfma_f32_32x32x16_bf16 v[80:95], v[212:215], v[140:143], 0
	ds_read_b128 v[208:211], v147 offset:32768
	ds_read_b128 v[212:215], v147 offset:40960
	v_exp_f32_e32 v66, v66
	v_exp_f32_e32 v67, v67
	v_cvt_pk_bf16_f32 v225, v226, v227
	s_waitcnt lgkmcnt(4)
	v_mfma_f32_32x32x16_bf16 v[96:111], v[216:219], v[136:139], v[96:111]
	v_exp_f32_e32 v68, v68
	v_exp_f32_e32 v69, v69
	v_cvt_pk_bf16_f32 v226, v228, v229
	v_mfma_f32_32x32x16_bf16 v[80:95], v[220:223], v[136:139], v[80:95]
	ds_read_b128 v[216:219], v148 offset:32768
	ds_read_b128 v[220:223], v148 offset:40960
	v_exp_f32_e32 v70, v70
	v_exp_f32_e32 v71, v71
	v_cvt_pk_bf16_f32 v227, v230, v231
	v_add_f32_e32 v251, v64, v66
	s_waitcnt lgkmcnt(4)
	v_mfma_f32_32x32x16_bf16 v[96:111], v[240:243], v[132:135], v[96:111]
	v_exp_f32_e32 v72, v72
	v_exp_f32_e32 v73, v73
	v_add_f32_e32 v253, v65, v67
	v_mfma_f32_32x32x16_bf16 v[80:95], v[244:247], v[132:135], v[80:95]
	ds_read_b128 v[240:243], v149 offset:32768
	ds_read_b128 v[244:247], v149 offset:40960
	v_exp_f32_e32 v74, v74
	v_exp_f32_e32 v75, v75
	v_add_f32_e32 v251, v251, v68
	s_waitcnt lgkmcnt(4)
	v_mfma_f32_32x32x16_bf16 v[96:111], v[208:211], v[128:131], v[96:111]
	v_exp_f32_e32 v76, v76
	v_exp_f32_e32 v77, v77
	v_add_f32_e32 v253, v253, v69
	v_cvt_pk_bf16_f32 v228, v232, v233
	v_mfma_f32_32x32x16_bf16 v[80:95], v[212:215], v[128:131], v[80:95]
	ds_read_b128 v[208:211], v150 offset:32768
	ds_read_b128 v[212:215], v150 offset:40960
	v_exp_f32_e32 v78, v78
	v_exp_f32_e32 v79, v79
	v_add_f32_e32 v251, v251, v70
	v_cvt_pk_bf16_f32 v229, v234, v235
	s_waitcnt lgkmcnt(4)
	v_mfma_f32_32x32x16_bf16 v[96:111], v[216:219], v[124:127], v[96:111]
	v_add_f32_e32 v253, v253, v71
	v_cvt_pk_bf16_f32 v230, v236, v237
	v_cvt_pk_bf16_f32 v231, v238, v239
	v_add_f32_e32 v251, v251, v72
	v_mfma_f32_32x32x16_bf16 v[80:95], v[220:223], v[124:127], v[80:95]
	ds_read_b128 v[216:219], v151 offset:32768
	ds_read_b128 v[220:223], v151 offset:40960
	v_add_f32_e32 v253, v253, v73
	v_cvt_pk_bf16_f32 v232, v64, v65
	v_cvt_pk_bf16_f32 v233, v66, v67
	s_waitcnt lgkmcnt(4)
; #define SBAR() __builtin_amdgcn_sched_barrier(0)
; __device__ __forceinline__ void partialSM_fix(f32x16& p0) { for (int r = 0; r < 16; ++r) p0[r] = __builtin_amdgcn_exp2f(p0[r]); }
; #define SLOAD(i, k0) do { sr_[i].vs0 = St::ld8(&Vh[(long)((k0) + sr) * LDK + sc]); sr_[i].vs1 = St::ld8(&Vh[(long)((k0) + 32 + sr) * LDK + sc]); \
;     sr_[i].ks0 = St::ld8(&Kh[(long)((k0) + sr) * LDK + sc]); sr_[i].ks1 = St::ld8(&Kh[(long)((k0) + 32 + sr) * LDK + sc]); } while (0)
; #define SWAIT() do { if constexpr (SDEPTH == 2) asm volatile("s_waitcnt vmcnt(4)" ::: "memory"); else asm volatile("s_waitcnt vmcnt(0)" ::: "memory"); } while (0)
; template <int D0> __device__ __forceinline__ void pv_one(f32x16& od, int vb, bf16x8 pa0, bf16x8 pa1, bf16x8 pa2, bf16x8 pa3) {
;   const s16x4 l0 = tr_read<v_rd_off(D0, 0, 0)>(vb), h0 = tr_read<v_rd_off(D0, 0, 1)>(vb), l1 = tr_read<v_rd_off(D0, 1, 0)>(vb), h1 = tr_read<v_rd_off(D0, 1, 1)>(vb);
;   const s16x4 l2 = tr_read<v_rd_off(D0, 2, 0)>(vb), h2 = tr_read<v_rd_off(D0, 2, 1)>(vb), l3 = tr_read<v_rd_off(D0, 3, 0)>(vb), h3 = tr_read<v_rd_off(D0, 3, 1)>(vb);
;   asm volatile("s_waitcnt lgkmcnt(0)" ::: "memory"); SBAR();
;     ...
;   od = __builtin_amdgcn_mfma_f32_32x32x16_bf16(pa0, PK(l0, h0), od, 0, 0, 0);
;   od = __builtin_amdgcn_mfma_f32_32x32x16_bf16(pa1, PK(l1, h1), od, 0, 0, 0);
;   od = __builtin_amdgcn_mfma_f32_32x32x16_bf16(pa2, PK(l2, h2), od, 0, 0, 0);
;   od = __builtin_amdgcn_mfma_f32_32x32x16_bf16(pa3, PK(l3, h3), od, 0, 0, 0);
;     ...
; }
; __device__ __forceinline__ void pv_d0(f32x16* o, int vb, bf16x8 pa0, bf16x8 pa1, bf16x8 pa2, bf16x8 pa3) {
;   pv_one<0>(o[0], vb, pa0, pa1, pa2, pa3); pv_one<1>(o[1], vb, pa0, pa1, pa2, pa3); pv_one<2>(o[2], vb, pa0, pa1, pa2, pa3); pv_one<3>(o[3], vb, pa0, pa1, pa2, pa3);
; }
; template <typename TQ>
; __device__ __forceinline__ void attn_dense_body(const TQ* __restrict__ Qb, const bf16* __restrict__ Kh, const bf16* __restrict__ Vh,
;                                                 bf16* __restrict__ Ob, int seq, char* lds) {
;     ...
;     SBAR(); qkt(pB0, pB1, (bf16*)((char*)K_lds + cur * (int)SHM_K), qr, r32, hi);
;     finishSM(pA0, pA1, alA, l_reg, pa0, pa1, pa2, pa3); SBAR();
;     SWAIT(); SWRITE(next, SE);
;     if (j + 2 < NT) SLOAD(SO, (j + 2) * KVBLK); SBAR();
;     pv_d0(o, vb0 + prev * (int)SHM_V, pa0, pa1, pa2, pa3); partialSM_fix(pB0);
;     __syncthreads();
	v_mfma_f32_32x32x16_bf16 v[96:111], v[240:243], v[120:123], v[96:111]
	v_add_f32_e32 v251, v251, v74
	v_cvt_pk_bf16_f32 v234, v68, v69
	v_cvt_pk_bf16_f32 v235, v70, v71
	v_mfma_f32_32x32x16_bf16 v[80:95], v[244:247], v[120:123], v[80:95]
	ds_read_b64_tr_b16 v[240:241], v179 offset:16384
	ds_read_b64_tr_b16 v[242:243], v179 offset:18432
	ds_read_b64_tr_b16 v[244:245], v179 offset:20480
	ds_read_b64_tr_b16 v[246:247], v179 offset:22528
	v_add_f32_e32 v253, v253, v75
	v_add_f32_e32 v251, v251, v76
	v_cvt_pk_bf16_f32 v236, v72, v73
	v_cvt_pk_bf16_f32 v237, v74, v75
	s_waitcnt lgkmcnt(6)
	v_mfma_f32_32x32x16_bf16 v[96:111], v[208:211], v[116:119], v[96:111]
	v_add_f32_e32 v253, v253, v77
	v_add_f32_e32 v251, v251, v78
	v_mfma_f32_32x32x16_bf16 v[80:95], v[212:215], v[116:119], v[80:95]
	ds_read_b64_tr_b16 v[208:209], v179 offset:24576
	ds_read_b64_tr_b16 v[210:211], v179 offset:26624
	ds_read_b64_tr_b16 v[212:213], v179 offset:28672
	ds_read_b64_tr_b16 v[214:215], v179 offset:30720
	v_add_f32_e32 v253, v253, v79
	v_cvt_pk_bf16_f32 v238, v76, v77
	v_cvt_pk_bf16_f32 v239, v78, v79
	s_waitcnt lgkmcnt(8)
	v_mfma_f32_32x32x16_bf16 v[96:111], v[216:219], v[112:115], v[96:111]
	v_add_f32_e32 v251, v251, v253
	v_add_f32_e32 v254, v254, v251
	v_mfma_f32_32x32x16_bf16 v[80:95], v[220:223], v[112:115], v[80:95]
	ds_read_b64_tr_b16 v[216:217], v179 offset:16896
	ds_read_b64_tr_b16 v[218:219], v179 offset:18944
	ds_read_b64_tr_b16 v[220:221], v179 offset:20992
	ds_read_b64_tr_b16 v[222:223], v179 offset:23040
	v_add_f32_e32 v169, v169, v254
	s_waitcnt lgkmcnt(10)
	v_mfma_f32_32x32x16_bf16 v[0:15], v[224:227], v[240:243], v[0:15]
	ds_read_b64_tr_b16 v[64:65], v179 offset:25088
	ds_read_b64_tr_b16 v[66:67], v179 offset:27136
	s_waitcnt lgkmcnt(10)
	v_mfma_f32_32x32x16_bf16 v[0:15], v[228:231], v[244:247], v[0:15]
	ds_read_b64_tr_b16 v[68:69], v179 offset:29184
	ds_read_b64_tr_b16 v[70:71], v179 offset:31232
	v_exp_f32_e32 v96, v96
	v_exp_f32_e32 v97, v97
	s_waitcnt lgkmcnt(10)
	v_mfma_f32_32x32x16_bf16 v[0:15], v[232:235], v[208:211], v[0:15]
	ds_read_b64_tr_b16 v[72:73], v179 offset:17408
	ds_read_b64_tr_b16 v[74:75], v179 offset:19456
	v_exp_f32_e32 v98, v98
	v_exp_f32_e32 v99, v99
	s_waitcnt lgkmcnt(10)
	v_mfma_f32_32x32x16_bf16 v[0:15], v[236:239], v[212:215], v[0:15]
	ds_read_b64_tr_b16 v[76:77], v179 offset:21504
	ds_read_b64_tr_b16 v[78:79], v179 offset:23552
	v_exp_f32_e32 v100, v100
	v_exp_f32_e32 v101, v101
	v_add_f32_e32 v254, v96, v98
	s_waitcnt lgkmcnt(10)
	v_mfma_f32_32x32x16_bf16 v[16:31], v[224:227], v[216:219], v[16:31]
	ds_read_b64_tr_b16 v[240:241], v179 offset:25600
	ds_read_b64_tr_b16 v[242:243], v179 offset:27648
	v_exp_f32_e32 v102, v102
	v_exp_f32_e32 v103, v103
	v_add_f32_e32 v255, v97, v99
	s_waitcnt lgkmcnt(10)
	v_mfma_f32_32x32x16_bf16 v[16:31], v[228:231], v[220:223], v[16:31]
	ds_read_b64_tr_b16 v[244:245], v179 offset:29696
	ds_read_b64_tr_b16 v[246:247], v179 offset:31744
	v_exp_f32_e32 v104, v104
	v_exp_f32_e32 v105, v105
	v_add_f32_e32 v254, v254, v100
	s_waitcnt lgkmcnt(10)
	v_mfma_f32_32x32x16_bf16 v[16:31], v[232:235], v[64:67], v[16:31]
	ds_read_b64_tr_b16 v[64:65], v179 offset:17920
	ds_read_b64_tr_b16 v[66:67], v179 offset:19968
	v_exp_f32_e32 v106, v106
	v_exp_f32_e32 v107, v107
	v_add_f32_e32 v255, v255, v101
	s_waitcnt lgkmcnt(10)
	v_mfma_f32_32x32x16_bf16 v[16:31], v[236:239], v[68:71], v[16:31]
	ds_read_b64_tr_b16 v[68:69], v179 offset:22016
	ds_read_b64_tr_b16 v[70:71], v179 offset:24064
	v_exp_f32_e32 v108, v108
	v_exp_f32_e32 v109, v109
	v_add_f32_e32 v254, v254, v102
	s_waitcnt lgkmcnt(10)
	v_mfma_f32_32x32x16_bf16 v[32:47], v[224:227], v[72:75], v[32:47]
	ds_read_b64_tr_b16 v[72:73], v179 offset:26112
	ds_read_b64_tr_b16 v[74:75], v179 offset:28160
	v_exp_f32_e32 v110, v110
	v_exp_f32_e32 v111, v111
	v_add_f32_e32 v255, v255, v103
	s_waitcnt lgkmcnt(10)
	v_mfma_f32_32x32x16_bf16 v[32:47], v[228:231], v[76:79], v[32:47]
	ds_read_b64_tr_b16 v[76:77], v179 offset:30208
	ds_read_b64_tr_b16 v[78:79], v179 offset:32256
	v_add_f32_e32 v254, v254, v104
	v_add_f32_e32 v255, v255, v105
	v_add_f32_e32 v254, v254, v106
	s_waitcnt lgkmcnt(10)
	v_mfma_f32_32x32x16_bf16 v[32:47], v[232:235], v[240:243], v[32:47]
	v_add_f32_e32 v255, v255, v107
	v_add_f32_e32 v254, v254, v108
	v_add_f32_e32 v255, v255, v109
	s_waitcnt lgkmcnt(8)
	v_mfma_f32_32x32x16_bf16 v[32:47], v[236:239], v[244:247], v[32:47]
	v_add_f32_e32 v254, v254, v110
	v_add_f32_e32 v255, v255, v111
	s_waitcnt vmcnt(0)
	s_waitcnt lgkmcnt(0)
	s_barrier
; #define SBAR() __builtin_amdgcn_sched_barrier(0)
; __device__ __forceinline__ void partialSM_fix(f32x16& p0) { for (int r = 0; r < 16; ++r) p0[r] = __builtin_amdgcn_exp2f(p0[r]); }
; #define SLOAD(i, k0) do { sr_[i].vs0 = St::ld8(&Vh[(long)((k0) + sr) * LDK + sc]); sr_[i].vs1 = St::ld8(&Vh[(long)((k0) + 32 + sr) * LDK + sc]); \
;     sr_[i].ks0 = St::ld8(&Kh[(long)((k0) + sr) * LDK + sc]); sr_[i].ks1 = St::ld8(&Kh[(long)((k0) + 32 + sr) * LDK + sc]); } while (0)
; #define SWAIT() do { if constexpr (SDEPTH == 2) asm volatile("s_waitcnt vmcnt(4)" ::: "memory"); else asm volatile("s_waitcnt vmcnt(0)" ::: "memory"); } while (0)
; template <typename TQ>
; __device__ __forceinline__ void attn_dense_body(const TQ* __restrict__ Qb, const bf16* __restrict__ Kh, const bf16* __restrict__ Vh,
;                                                 bf16* __restrict__ Ob, int seq, char* lds) {
;     ...
;     SBAR(); qkt(pA0, pA1, (bf16*)((char*)K_lds + cur * (int)SHM_K), qr, r32, hi);
;     finishSM(pB0, pB1, alB, l_reg, pa0, pa1, pa2, pa3); SBAR();
;     if (j + 2 < NT) { SWAIT(); SWRITE(next, SO); }
;     if (j + 3 < NT) SLOAD(SE, (j + 3) * KVBLK); SBAR();
;     pv_d0(o, vb0 + prev * (int)SHM_V, pa0, pa1, pa2, pa3); partialSM_fix(pA0);
	ds_read_b128 v[208:211], v144 offset:0
	ds_read_b128 v[212:215], v144 offset:8192
	ds_read_b128 v[216:219], v145 offset:0
	ds_read_b128 v[220:223], v145 offset:8192
	ds_read_b128 v[240:243], v146 offset:0
	ds_read_b128 v[244:247], v146 offset:8192
	v_mfma_f32_32x32x16_bf16 v[48:63], v[224:227], v[64:67], v[48:63]
	v_add_f32_e32 v254, v254, v255
	s_add_i32 m0, s80, 0x4000
	s_add_u32 s96, s90, 0x80
	s_addc_u32 s97, s91, 0
	global_load_lds_dwordx4 v249, s[90:91]
	v_mfma_f32_32x32x16_bf16 v[48:63], v[228:231], v[68:71], v[48:63]
	s_add_i32 m0, s81, 0x4000
	s_nop 0
	global_load_lds_dwordx4 v249, s[96:97]
	v_mfma_f32_32x32x16_bf16 v[48:63], v[232:235], v[72:75], v[48:63]
	s_add_i32 m0, s82, 0x4000
	s_nop 0
	global_load_lds_dwordx4 v174, s[92:93]
	v_mfma_f32_32x32x16_bf16 v[48:63], v[236:239], v[76:79], v[48:63]
	s_add_i32 m0, s83, 0x4000
	s_add_u32 s90, s90, 0x4000
	global_load_lds_dwordx4 v175, s[92:93]
	s_addc_u32 s91, s91, 0
	s_add_u32 s92, s92, 0x4000
	s_addc_u32 s93, s93, 0
	s_waitcnt lgkmcnt(4)
	v_mfma_f32_32x32x16_bf16 v[224:239], v[208:211], v[140:143], 0
	v_exp_f32_e32 v80, v80
	v_exp_f32_e32 v81, v81
	v_cvt_pk_bf16_f32 v96, v96, v97
	v_mfma_f32_32x32x16_bf16 v[64:79], v[212:215], v[140:143], 0
	ds_read_b128 v[208:211], v147 offset:0
	ds_read_b128 v[212:215], v147 offset:8192
	v_exp_f32_e32 v82, v82
	v_exp_f32_e32 v83, v83
	v_cvt_pk_bf16_f32 v97, v98, v99
	s_waitcnt lgkmcnt(4)
	v_mfma_f32_32x32x16_bf16 v[224:239], v[216:219], v[136:139], v[224:239]
	v_exp_f32_e32 v84, v84
	v_exp_f32_e32 v85, v85
	v_cvt_pk_bf16_f32 v98, v100, v101
	v_mfma_f32_32x32x16_bf16 v[64:79], v[220:223], v[136:139], v[64:79]
	ds_read_b128 v[216:219], v148 offset:0
	ds_read_b128 v[220:223], v148 offset:8192
	v_exp_f32_e32 v86, v86
	v_exp_f32_e32 v87, v87
	v_cvt_pk_bf16_f32 v99, v102, v103
	v_add_f32_e32 v251, v80, v82
	s_waitcnt lgkmcnt(4)
	v_mfma_f32_32x32x16_bf16 v[224:239], v[240:243], v[132:135], v[224:239]
	v_exp_f32_e32 v88, v88
	v_exp_f32_e32 v89, v89
	v_add_f32_e32 v253, v81, v83
	v_mfma_f32_32x32x16_bf16 v[64:79], v[244:247], v[132:135], v[64:79]
	ds_read_b128 v[240:243], v149 offset:0
	ds_read_b128 v[244:247], v149 offset:8192
	v_exp_f32_e32 v90, v90
	v_exp_f32_e32 v91, v91
	v_add_f32_e32 v251, v251, v84
	s_waitcnt lgkmcnt(4)
	v_mfma_f32_32x32x16_bf16 v[224:239], v[208:211], v[128:131], v[224:239]
	v_exp_f32_e32 v92, v92
	v_exp_f32_e32 v93, v93
	v_add_f32_e32 v253, v253, v85
	v_cvt_pk_bf16_f32 v100, v104, v105
	v_mfma_f32_32x32x16_bf16 v[64:79], v[212:215], v[128:131], v[64:79]
	ds_read_b128 v[208:211], v150 offset:0
	ds_read_b128 v[212:215], v150 offset:8192
	v_exp_f32_e32 v94, v94
	v_exp_f32_e32 v95, v95
	v_add_f32_e32 v251, v251, v86
	v_cvt_pk_bf16_f32 v101, v106, v107
	s_waitcnt lgkmcnt(4)
	v_mfma_f32_32x32x16_bf16 v[224:239], v[216:219], v[124:127], v[224:239]
	v_add_f32_e32 v253, v253, v87
	v_cvt_pk_bf16_f32 v102, v108, v109
	v_cvt_pk_bf16_f32 v103, v110, v111
	v_add_f32_e32 v251, v251, v88
	v_mfma_f32_32x32x16_bf16 v[64:79], v[220:223], v[124:127], v[64:79]
	ds_read_b128 v[216:219], v151 offset:0
	ds_read_b128 v[220:223], v151 offset:8192
	v_add_f32_e32 v253, v253, v89
	v_cvt_pk_bf16_f32 v104, v80, v81
	v_cvt_pk_bf16_f32 v105, v82, v83
	s_waitcnt lgkmcnt(4)
	v_mfma_f32_32x32x16_bf16 v[224:239], v[240:243], v[120:123], v[224:239]
	v_add_f32_e32 v251, v251, v90
	v_cvt_pk_bf16_f32 v106, v84, v85
	v_cvt_pk_bf16_f32 v107, v86, v87
	v_mfma_f32_32x32x16_bf16 v[64:79], v[244:247], v[120:123], v[64:79]
	ds_read_b64_tr_b16 v[240:241], v179 offset:32768
	ds_read_b64_tr_b16 v[242:243], v179 offset:34816
	ds_read_b64_tr_b16 v[244:245], v179 offset:36864
	ds_read_b64_tr_b16 v[246:247], v179 offset:38912
	v_add_f32_e32 v253, v253, v91
	v_add_f32_e32 v251, v251, v92
	v_cvt_pk_bf16_f32 v108, v88, v89
	v_cvt_pk_bf16_f32 v109, v90, v91
	s_waitcnt lgkmcnt(6)
	v_mfma_f32_32x32x16_bf16 v[224:239], v[208:211], v[116:119], v[224:239]
	v_add_f32_e32 v253, v253, v93
	v_add_f32_e32 v251, v251, v94
	v_mfma_f32_32x32x16_bf16 v[64:79], v[212:215], v[116:119], v[64:79]
	ds_read_b64_tr_b16 v[208:209], v179 offset:40960
	ds_read_b64_tr_b16 v[210:211], v179 offset:43008
	ds_read_b64_tr_b16 v[212:213], v179 offset:45056
	ds_read_b64_tr_b16 v[214:215], v179 offset:47104
	v_add_f32_e32 v253, v253, v95
	v_cvt_pk_bf16_f32 v110, v92, v93
	v_cvt_pk_bf16_f32 v111, v94, v95
	s_waitcnt lgkmcnt(8)
	v_mfma_f32_32x32x16_bf16 v[224:239], v[216:219], v[112:115], v[224:239]
	v_add_f32_e32 v251, v251, v253
	v_add_f32_e32 v254, v254, v251
	v_mfma_f32_32x32x16_bf16 v[64:79], v[220:223], v[112:115], v[64:79]
	ds_read_b64_tr_b16 v[216:217], v179 offset:33280
	ds_read_b64_tr_b16 v[218:219], v179 offset:35328
	ds_read_b64_tr_b16 v[220:221], v179 offset:37376
	ds_read_b64_tr_b16 v[222:223], v179 offset:39424
	v_add_f32_e32 v169, v169, v254
	s_waitcnt lgkmcnt(10)
; #define SBAR() __builtin_amdgcn_sched_barrier(0)
; __device__ __forceinline__ void partialSM_fix(f32x16& p0) { for (int r = 0; r < 16; ++r) p0[r] = __builtin_amdgcn_exp2f(p0[r]); }
; #define SLOAD(i, k0) do { sr_[i].vs0 = St::ld8(&Vh[(long)((k0) + sr) * LDK + sc]); sr_[i].vs1 = St::ld8(&Vh[(long)((k0) + 32 + sr) * LDK + sc]); \
;     sr_[i].ks0 = St::ld8(&Kh[(long)((k0) + sr) * LDK + sc]); sr_[i].ks1 = St::ld8(&Kh[(long)((k0) + 32 + sr) * LDK + sc]); } while (0)
; #define SWAIT() do { if constexpr (SDEPTH == 2) asm volatile("s_waitcnt vmcnt(4)" ::: "memory"); else asm volatile("s_waitcnt vmcnt(0)" ::: "memory"); } while (0)
; template <typename TQ>
; __device__ __forceinline__ void attn_dense_body(const TQ* __restrict__ Qb, const bf16* __restrict__ Kh, const bf16* __restrict__ Vh,
;                                                 bf16* __restrict__ Ob, int seq, char* lds) {
;     ...
;     SBAR(); qkt(pA0, pA1, (bf16*)((char*)K_lds + cur * (int)SHM_K), qr, r32, hi);
;     finishSM(pB0, pB1, alB, l_reg, pa0, pa1, pa2, pa3); SBAR();
;     if (j + 2 < NT) { SWAIT(); SWRITE(next, SO); }
;     if (j + 3 < NT) SLOAD(SE, (j + 3) * KVBLK); SBAR();
;     pv_d0(o, vb0 + prev * (int)SHM_V, pa0, pa1, pa2, pa3); partialSM_fix(pA0);
;     __syncthreads();
;     { const int t_ = prev; prev = cur; cur = next; next = t_; }
;   }
;   SBAR(); qkt(pB0, pB1, (bf16*)((char*)K_lds + cur * (int)SHM_K), qr, r32, hi);
	v_mfma_f32_32x32x16_bf16 v[0:15], v[96:99], v[240:243], v[0:15]
	ds_read_b64_tr_b16 v[80:81], v179 offset:41472
	ds_read_b64_tr_b16 v[82:83], v179 offset:43520
	s_waitcnt lgkmcnt(10)
	v_mfma_f32_32x32x16_bf16 v[0:15], v[100:103], v[244:247], v[0:15]
	ds_read_b64_tr_b16 v[84:85], v179 offset:45568
	ds_read_b64_tr_b16 v[86:87], v179 offset:47616
	v_exp_f32_e32 v224, v224
	v_exp_f32_e32 v225, v225
	s_waitcnt lgkmcnt(10)
	v_mfma_f32_32x32x16_bf16 v[0:15], v[104:107], v[208:211], v[0:15]
	ds_read_b64_tr_b16 v[88:89], v179 offset:33792
	ds_read_b64_tr_b16 v[90:91], v179 offset:35840
	v_exp_f32_e32 v226, v226
	v_exp_f32_e32 v227, v227
	s_waitcnt lgkmcnt(10)
	v_mfma_f32_32x32x16_bf16 v[0:15], v[108:111], v[212:215], v[0:15]
	ds_read_b64_tr_b16 v[92:93], v179 offset:37888
	ds_read_b64_tr_b16 v[94:95], v179 offset:39936
	v_exp_f32_e32 v228, v228
	v_exp_f32_e32 v229, v229
	v_add_f32_e32 v254, v224, v226
	s_waitcnt lgkmcnt(10)
	v_mfma_f32_32x32x16_bf16 v[16:31], v[96:99], v[216:219], v[16:31]
	ds_read_b64_tr_b16 v[240:241], v179 offset:41984
	ds_read_b64_tr_b16 v[242:243], v179 offset:44032
	v_exp_f32_e32 v230, v230
	v_exp_f32_e32 v231, v231
	v_add_f32_e32 v255, v225, v227
	s_waitcnt lgkmcnt(10)
	v_mfma_f32_32x32x16_bf16 v[16:31], v[100:103], v[220:223], v[16:31]
	ds_read_b64_tr_b16 v[244:245], v179 offset:46080
	ds_read_b64_tr_b16 v[246:247], v179 offset:48128
	v_exp_f32_e32 v232, v232
	v_exp_f32_e32 v233, v233
	v_add_f32_e32 v254, v254, v228
	s_waitcnt lgkmcnt(10)
	v_mfma_f32_32x32x16_bf16 v[16:31], v[104:107], v[80:83], v[16:31]
	ds_read_b64_tr_b16 v[80:81], v179 offset:34304
	ds_read_b64_tr_b16 v[82:83], v179 offset:36352
	v_exp_f32_e32 v234, v234
	v_exp_f32_e32 v235, v235
	v_add_f32_e32 v255, v255, v229
	s_waitcnt lgkmcnt(10)
	v_mfma_f32_32x32x16_bf16 v[16:31], v[108:111], v[84:87], v[16:31]
	ds_read_b64_tr_b16 v[84:85], v179 offset:38400
	ds_read_b64_tr_b16 v[86:87], v179 offset:40448
	v_exp_f32_e32 v236, v236
	v_exp_f32_e32 v237, v237
	v_add_f32_e32 v254, v254, v230
	s_waitcnt lgkmcnt(10)
	v_mfma_f32_32x32x16_bf16 v[32:47], v[96:99], v[88:91], v[32:47]
	ds_read_b64_tr_b16 v[88:89], v179 offset:42496
	ds_read_b64_tr_b16 v[90:91], v179 offset:44544
	v_exp_f32_e32 v238, v238
	v_exp_f32_e32 v239, v239
	v_add_f32_e32 v255, v255, v231
	s_waitcnt lgkmcnt(10)
	v_mfma_f32_32x32x16_bf16 v[32:47], v[100:103], v[92:95], v[32:47]
	ds_read_b64_tr_b16 v[92:93], v179 offset:46592
	ds_read_b64_tr_b16 v[94:95], v179 offset:48640
	v_add_f32_e32 v254, v254, v232
	v_add_f32_e32 v255, v255, v233
	v_add_f32_e32 v254, v254, v234
	s_waitcnt lgkmcnt(10)
	v_mfma_f32_32x32x16_bf16 v[32:47], v[104:107], v[240:243], v[32:47]
	v_add_f32_e32 v255, v255, v235
	v_add_f32_e32 v254, v254, v236
	v_add_f32_e32 v255, v255, v237
	s_waitcnt lgkmcnt(8)
	v_mfma_f32_32x32x16_bf16 v[32:47], v[108:111], v[244:247], v[32:47]
	v_add_f32_e32 v254, v254, v238
	v_add_f32_e32 v255, v255, v239
	s_waitcnt vmcnt(0)
	s_waitcnt lgkmcnt(0)
	s_barrier
	ds_read_b128 v[208:211], v144 offset:16384
	ds_read_b128 v[212:215], v144 offset:24576
	ds_read_b128 v[216:219], v145 offset:16384
	ds_read_b128 v[220:223], v145 offset:24576
	ds_read_b128 v[240:243], v146 offset:16384
	ds_read_b128 v[244:247], v146 offset:24576
	v_mfma_f32_32x32x16_bf16 v[48:63], v[96:99], v[80:83], v[48:63]
	v_add_f32_e32 v254, v254, v255
	s_cmp_ge_u32 s55, s53
	s_cbranch_scc1 .Latt_nodma0_i2
	s_add_i32 m0, s80, 0x8000
	s_add_u32 s96, s90, 0x80
	s_addc_u32 s97, s91, 0
	global_load_lds_dwordx4 v249, s[90:91]
.Latt_nodma0_i2:
	v_mfma_f32_32x32x16_bf16 v[48:63], v[100:103], v[84:87], v[48:63]
	s_cmp_ge_u32 s55, s53
	s_cbranch_scc1 .Latt_nodma1_i2
	s_add_i32 m0, s81, 0x8000
	s_nop 0
	global_load_lds_dwordx4 v249, s[96:97]
.Latt_nodma1_i2:
	v_mfma_f32_32x32x16_bf16 v[48:63], v[104:107], v[88:91], v[48:63]
	s_cmp_ge_u32 s55, s53
	s_cbranch_scc1 .Latt_nodma2_i2
	s_add_i32 m0, s82, 0x8000
	s_nop 0
	global_load_lds_dwordx4 v174, s[92:93]
.Latt_nodma2_i2:
	v_mfma_f32_32x32x16_bf16 v[48:63], v[108:111], v[92:95], v[48:63]
	s_cmp_ge_u32 s55, s53
	s_cbranch_scc1 .Latt_nodma3_i2
	s_add_i32 m0, s83, 0x8000
	s_add_u32 s90, s90, 0x4000
	global_load_lds_dwordx4 v175, s[92:93]
	s_addc_u32 s91, s91, 0
	s_add_u32 s92, s92, 0x4000
	s_addc_u32 s93, s93, 0
.Latt_nodma3_i2:
	s_add_i32 s55, s55, 2
	s_cmp_ge_u32 s55, s32
	s_cbranch_scc1 .Latt_exit_2
	s_branch .Latt_loop
.Latt_exit_0:
	s_mov_b32 s20, 0x0
	s_mov_b32 s18, 0x8000
	s_branch .Latt_exit
.Latt_exit_1:
	s_mov_b32 s20, 0x8000
	s_mov_b32 s18, 0x4000
	s_branch .Latt_exit
.Latt_exit_2:
	s_mov_b32 s20, 0x4000
	s_mov_b32 s18, 0x0
